# phase 1 in-proj GEMM (first 2048 tiles) on the shared-A tile-pair ring with hand-written plain/RMS-norm/transposed epilogues; phase 5 K/V staging and phase 0 w_in guarded loads de-serialised
# speedup vs baseline: 1.1694x; 1.0258x over previous
.LBB0_180:
	v_mov_b32_e32 v86, v131
	s_barrier
	s_lshl_b32 s82, s29, 6
	v_ashrrev_i32_e32 v4, 4, v86
	v_ashrrev_i32_e32 v5, 31, v4
	v_lshlrev_b64 v[6:7], 10, v[4:5]
	v_add_u32_e32 v5, 0x100, v86
	v_ashrrev_i32_e32 v8, 4, v5
	v_ashrrev_i32_e32 v9, 31, v8
	v_lshlrev_b64 v[10:11], 10, v[8:9]
	v_add_u32_e32 v9, 0x200, v86
	v_ashrrev_i32_e32 v12, 4, v9
	s_lshl_b64 s[30:31], s[82:83], 10
	v_ashrrev_i32_e32 v13, 31, v12
	s_add_u32 s30, s23, s30
	v_lshlrev_b64 v[14:15], 10, v[12:13]
	v_add_u32_e32 v13, 0x300, v86
	s_addc_u32 s31, s24, s31
	s_lshl_b32 s34, s29, 7
	v_lshlrev_b32_e32 v84, 4, v86
	v_ashrrev_i32_e32 v80, 4, v13
	s_add_u32 s40, s25, s34
	v_and_b32_e32 v0, 0xf0, v84
	v_ashrrev_i32_e32 v81, 31, v80
	v_ashrrev_i32_e32 v86, 3, v86
	v_ashrrev_i32_e32 v90, 3, v5
	v_ashrrev_i32_e32 v94, 3, v9
	v_ashrrev_i32_e32 v142, 3, v13
	s_addc_u32 s41, s28, 0
	v_lshl_add_u64 v[2:3], s[30:31], 0, v[0:1]
	v_lshlrev_b64 v[82:83], 10, v[80:81]
	v_and_b32_e32 v84, 0x70, v84
	v_mov_b32_e32 v85, v1
	v_ashrrev_i32_e32 v87, 31, v86
	v_ashrrev_i32_e32 v91, 31, v90
	v_ashrrev_i32_e32 v95, 31, v94
	v_ashrrev_i32_e32 v143, 31, v142
	v_lshl_add_u64 v[6:7], v[2:3], 0, v[6:7]
	v_lshl_add_u64 v[10:11], v[2:3], 0, v[10:11]
	v_lshl_add_u64 v[14:15], v[2:3], 0, v[14:15]
	v_lshl_add_u64 v[82:83], v[2:3], 0, v[82:83]
	v_lshl_add_u64 v[2:3], s[40:41], 0, v[84:85]
	v_lshlrev_b64 v[88:89], 9, v[86:87]
	v_lshlrev_b64 v[92:93], 9, v[90:91]
	v_lshlrev_b64 v[140:141], 9, v[94:95]
	v_lshlrev_b64 v[144:145], 9, v[142:143]
	v_add_u32_e32 v0, 16, v0
	v_lshl_add_u64 v[88:89], v[2:3], 0, v[88:89]
	v_lshl_add_u64 v[92:93], v[2:3], 0, v[92:93]
	v_lshl_add_u64 v[140:141], v[2:3], 0, v[140:141]
	v_lshl_add_u64 v[144:145], v[2:3], 0, v[144:145]
	v_mad_u64_u32 v[146:147], s[30:31], v4, s36, v[0:1]
	v_mad_u64_u32 v[196:197], s[30:31], v8, s36, v[0:1]
	v_mad_u64_u32 v[198:199], s[30:31], v12, s36, v[0:1]
	v_mad_u64_u32 v[200:201], s[30:31], v80, s36, v[0:1]
	global_load_dwordx4 v[212:215], v[6:7], off
	global_load_dwordx4 v[216:219], v[10:11], off
	global_load_dwordx4 v[220:223], v[14:15], off
	global_load_dwordx4 v[224:227], v[82:83], off
	global_load_dwordx4 v[228:231], v[88:89], off
	global_load_dwordx4 v[232:235], v[92:93], off
	global_load_dwordx4 v[236:239], v[140:141], off
	global_load_dwordx4 v[240:243], v[144:145], off
	v_add_u32_e32 v0, 16, v84
	v_mad_u64_u32 v[202:203], s[30:31], v86, s9, v[0:1]
	v_mad_u64_u32 v[204:205], s[30:31], v90, s9, v[0:1]
	v_mad_u64_u32 v[206:207], s[30:31], v94, s9, v[0:1]
	v_mad_u64_u32 v[244:245], s[30:31], v142, s9, v[0:1]
	s_mov_b64 s[40:41], -1
	s_nop 1
	s_mov_b32 s30, 0
	s_waitcnt vmcnt(7)
	ds_write_b128 v146, v[212:215]
	s_waitcnt vmcnt(6)
	ds_write_b128 v196, v[216:219]
	s_waitcnt vmcnt(5)
	ds_write_b128 v198, v[220:223]
	s_waitcnt vmcnt(4)
	ds_write_b128 v200, v[224:227]
	s_waitcnt vmcnt(3)
	ds_write_b128 v202, v[228:231] offset:17408
	s_waitcnt vmcnt(2)
	ds_write_b128 v204, v[232:235] offset:17408
	s_waitcnt vmcnt(1)
	ds_write_b128 v206, v[236:239] offset:17408
	s_waitcnt vmcnt(0)
	ds_write_b128 v244, v[240:243] offset:17408
	s_waitcnt lgkmcnt(0)
	s_barrier

.LBB0_235:
	s_andn2_b64 vcc, exec, s[40:41]
	s_cbranch_vccnz .LBB0_357
	v_readlane_b32 s20, v210, 53
	v_readlane_b32 s21, v210, 54
	s_andn2_b64 vcc, exec, s[20:21]
	s_mov_b64 s[40:41], -1
	s_cbranch_vccnz .LBB0_328
	s_mov_b32 s8, 0
	s_branch .LBB0_239
.Ltramp7a:
	s_branch .LBB0_7
.LBB0_238:
	s_or_b64 exec, exec, s[40:41]
	s_addk_i32 s8, 0x600
	s_cmpk_eq_i32 s8, 0x1e00
	s_cbranch_scc1 .LBB0_327

.LBB0_362:
	s_andn2_b64 vcc, exec, s[40:41]
	s_cbranch_vccnz .Ltramp7a
	v_readlane_b32 s20, v209, 10
	v_readlane_b32 s21, v209, 11
	s_andn2_b64 vcc, exec, s[20:21]
	s_cbranch_vccnz .Ltramp7a
	s_add_u32 s46, s12, 8
	s_addc_u32 s47, s13, 0
	s_mov_b32 s8, s60
	s_branch .LBB0_489
.Ltramp7b:
	s_branch .Ltramp7a
.Lin2_entry:
	s_mov_b32 s21, s60
	s_cmpk_gt_i32 s21, 0x1ff
	s_cbranch_scc1 .Lin2_done

.Lin2_tile:
	s_load_dwordx2 s[44:45], s[12:13], 0x160
	s_load_dwordx2 s[46:47], s[12:13], 0x108
	s_bfe_u32 s53, s21, 0x30006
	s_lshl_b32 s53, s53, 3
	s_and_b32 s56, s21, 7
	s_or_b32 s53, s53, s56
	s_lshl_b32 s53, s53, 7
	s_bfe_u32 s54, s21, 0x30003
	s_lshl_b32 s56, s55, 4
	s_add_i32 s54, s54, s56
	s_lshl_b32 s54, s54, 7
	v_lshrrev_b32_e32 v241, 6, v131
	v_and_b32_e32 v242, 63, v131
	s_nop 0
	v_readfirstlane_b32 s50, v241
	v_lshrrev_b32_e32 v241, 3, v242
	v_lshrrev_b32_e32 v243, 4, v242
	v_and_b32_e32 v244, 7, v242
	s_movk_i32 s56, 0x1080
	v_xor_b32_e32 v245, v244, v243
	v_lshlrev_b32_e32 v245, 4, v245
	v_mad_u32_u24 v228, v241, s56, v245
	v_or_b32_e32 v243, 4, v243
	v_xor_b32_e32 v245, v244, v243
	v_lshlrev_b32_e32 v245, 4, v245
	v_add_u32_e32 v241, 8, v241
	v_mad_u32_u24 v230, v241, s56, v245
	v_add_u32_e32 v229, 0x42000, v228
	v_add_u32_e32 v231, 0x42000, v230
	v_and_b32_e32 v241, 15, v242
	v_lshrrev_b32_e32 v243, 4, v242
	v_bfe_u32 v244, v242, 1, 3
	v_xor_b32_e32 v244, v243, v244
	v_lshlrev_b32_e32 v244, 4, v244
	v_lshl_or_b32 v232, v241, 7, v244
	v_xor_b32_e32 v233, 64, v232
	s_lshr_b32 s56, s50, 1
	s_and_b32 s57, s50, 1
	s_mul_i32 s0, s56, 64*528
	s_lshl_b32 s52, s57, 8
	s_add_i32 s0, s0, s52
	s_add_i32 s0, s0, 16
	v_mul_u32_u24_e32 v243, 4*528, v243
	v_lshl_add_u32 v243, v241, 2, v243
	v_add_u32_e32 v238, s0, v243
	s_add_i32 s22, s56, 0
	s_lshl_b32 s22, s22, 13
	s_add_i32 s22, s22, 16
	s_add_i32 s28, s57, 2
	s_lshl_b32 s28, s28, 13
	s_add_i32 s28, s28, 16
	s_add_i32 s40, s57, 4
	s_lshl_b32 s40, s40, 13
	s_add_i32 s40, s40, 16
	s_add_i32 s23, s56, 6
	s_lshl_b32 s23, s23, 13
	s_add_i32 s23, s23, 16
	s_add_i32 s29, s57, 8
	s_cmp_ge_u32 s29, 9
	s_cselect_b32 s0, 9, 0
	s_sub_i32 s29, s29, s0
	s_lshl_b32 s29, s29, 13
	s_add_i32 s29, s29, 16
	s_add_i32 s41, s57, 1
	s_lshl_b32 s41, s41, 13
	s_add_i32 s41, s41, 16
	s_add_i32 s24, s56, 3
	s_lshl_b32 s24, s24, 13
	s_add_i32 s24, s24, 16
	s_add_i32 s30, s57, 5
	s_lshl_b32 s30, s30, 13
	s_add_i32 s30, s30, 16
	s_add_i32 s42, s57, 7
	s_lshl_b32 s42, s42, 13
	s_add_i32 s42, s42, 16
	s_lshl_b32 s56, s50, 4
	s_add_i32 s57, s53, s56
	s_add_i32 s56, s54, s56
	s_mul_i32 s57, s57, 0x1080
	s_mul_i32 s56, s56, 0x1080
	s_waitcnt lgkmcnt(0)
	s_add_u32 s44, s44, s57
	s_addc_u32 s45, s45, 0
	s_add_u32 s46, s46, s56
	s_addc_u32 s47, s47, 0
	s_add_u32 s48, s46, 0x420000
	s_addc_u32 s49, s47, 0
	s_lshl_b32 s51, s50, 11
	s_add_i32 s51, s51, 16
	v_mov_b32_e32 v2, 0
	v_mov_b32_e32 v3, 0
	v_mov_b32_e32 v4, 0
	v_mov_b32_e32 v5, 0
	v_mov_b32_e32 v6, 0
	v_mov_b32_e32 v7, 0
	v_mov_b32_e32 v8, 0
	v_mov_b32_e32 v9, 0
	v_mov_b32_e32 v10, 0
	v_mov_b32_e32 v11, 0
	v_mov_b32_e32 v12, 0
	v_mov_b32_e32 v13, 0
	v_mov_b32_e32 v14, 0
	v_mov_b32_e32 v15, 0
	v_mov_b32_e32 v16, 0
	v_mov_b32_e32 v17, 0
	v_mov_b32_e32 v18, 0
	v_mov_b32_e32 v19, 0
	v_mov_b32_e32 v20, 0
	v_mov_b32_e32 v21, 0
	v_mov_b32_e32 v22, 0
	v_mov_b32_e32 v23, 0
	v_mov_b32_e32 v24, 0
	v_mov_b32_e32 v25, 0
	v_mov_b32_e32 v26, 0
	v_mov_b32_e32 v27, 0
	v_mov_b32_e32 v28, 0
	v_mov_b32_e32 v29, 0
	v_mov_b32_e32 v30, 0
	v_mov_b32_e32 v31, 0
	v_mov_b32_e32 v32, 0
	v_mov_b32_e32 v33, 0
	v_mov_b32_e32 v34, 0
	v_mov_b32_e32 v35, 0
	v_mov_b32_e32 v36, 0
	v_mov_b32_e32 v37, 0
	v_mov_b32_e32 v38, 0
	v_mov_b32_e32 v39, 0
	v_mov_b32_e32 v40, 0
	v_mov_b32_e32 v41, 0
	v_mov_b32_e32 v42, 0
	v_mov_b32_e32 v43, 0
	v_mov_b32_e32 v44, 0
	v_mov_b32_e32 v45, 0
	v_mov_b32_e32 v46, 0
	v_mov_b32_e32 v47, 0
	v_mov_b32_e32 v48, 0
	v_mov_b32_e32 v49, 0
	v_mov_b32_e32 v50, 0
	v_mov_b32_e32 v51, 0
	v_mov_b32_e32 v52, 0
	v_mov_b32_e32 v53, 0
	v_mov_b32_e32 v54, 0
	v_mov_b32_e32 v55, 0
	v_mov_b32_e32 v56, 0
	v_mov_b32_e32 v57, 0
	v_mov_b32_e32 v58, 0
	v_mov_b32_e32 v59, 0
	v_mov_b32_e32 v60, 0
	v_mov_b32_e32 v61, 0
	v_mov_b32_e32 v62, 0
	v_mov_b32_e32 v63, 0
	v_mov_b32_e32 v64, 0
	v_mov_b32_e32 v65, 0
	v_mov_b32_e32 v66, 0
	v_mov_b32_e32 v67, 0
	v_mov_b32_e32 v68, 0
	v_mov_b32_e32 v69, 0
	v_mov_b32_e32 v70, 0
	v_mov_b32_e32 v71, 0
	v_mov_b32_e32 v72, 0
	v_mov_b32_e32 v73, 0
	v_mov_b32_e32 v74, 0
	v_mov_b32_e32 v75, 0
	v_mov_b32_e32 v76, 0
	v_mov_b32_e32 v77, 0
	v_mov_b32_e32 v78, 0
	v_mov_b32_e32 v79, 0
	v_mov_b32_e32 v80, 0
	v_mov_b32_e32 v81, 0
	v_mov_b32_e32 v82, 0
	v_mov_b32_e32 v83, 0
	v_mov_b32_e32 v84, 0
	v_mov_b32_e32 v85, 0
	v_mov_b32_e32 v86, 0
	v_mov_b32_e32 v87, 0
	v_mov_b32_e32 v88, 0
	v_mov_b32_e32 v89, 0
	v_mov_b32_e32 v90, 0
	v_mov_b32_e32 v91, 0
	v_mov_b32_e32 v92, 0
	v_mov_b32_e32 v93, 0
	v_mov_b32_e32 v94, 0
	v_mov_b32_e32 v95, 0
	v_mov_b32_e32 v96, 0
	v_mov_b32_e32 v97, 0
	v_mov_b32_e32 v98, 0
	v_mov_b32_e32 v99, 0
	v_mov_b32_e32 v100, 0
	v_mov_b32_e32 v101, 0
	v_mov_b32_e32 v102, 0
	v_mov_b32_e32 v103, 0
	v_mov_b32_e32 v104, 0
	v_mov_b32_e32 v105, 0
	v_mov_b32_e32 v106, 0
	v_mov_b32_e32 v107, 0
	v_mov_b32_e32 v108, 0
	v_mov_b32_e32 v109, 0
	v_mov_b32_e32 v110, 0
	v_mov_b32_e32 v111, 0
	v_mov_b32_e32 v112, 0
	v_mov_b32_e32 v113, 0
	v_mov_b32_e32 v114, 0
	v_mov_b32_e32 v115, 0
	v_mov_b32_e32 v116, 0
	v_mov_b32_e32 v117, 0
	v_mov_b32_e32 v118, 0
	v_mov_b32_e32 v119, 0
	v_mov_b32_e32 v120, 0
	v_mov_b32_e32 v121, 0
	v_mov_b32_e32 v122, 0
	v_mov_b32_e32 v123, 0
	v_mov_b32_e32 v124, 0
	v_mov_b32_e32 v125, 0
	v_mov_b32_e32 v126, 0
	v_mov_b32_e32 v127, 0
	v_mov_b32_e32 v128, 0
	v_mov_b32_e32 v129, 0
	s_barrier
	s_mov_b32 m0, s51
	s_nop 0
	global_load_lds_dwordx4 v228, s[44:45]
	s_add_i32 m0, s51, 0x400
	s_nop 0
	global_load_lds_dwordx4 v230, s[44:45]
	s_add_i32 m0, s51, 0x2000
	s_nop 0
	global_load_lds_dwordx4 v229, s[44:45]
	s_add_i32 m0, s51, 0x2400
	s_nop 0
	global_load_lds_dwordx4 v231, s[44:45]
	s_add_i32 m0, s51, 0x4000
	s_nop 0
	global_load_lds_dwordx4 v228, s[46:47]
	s_add_i32 m0, s51, 0x4400
	s_nop 0
	global_load_lds_dwordx4 v230, s[46:47]
	s_add_i32 m0, s51, 0x6000
	s_nop 0
	global_load_lds_dwordx4 v229, s[46:47]
	s_add_i32 m0, s51, 0x6400
	s_nop 0
	global_load_lds_dwordx4 v231, s[46:47]
	s_add_i32 m0, s51, 0x8000
	s_nop 0
	global_load_lds_dwordx4 v228, s[48:49]
	s_add_i32 m0, s51, 0x8400
	s_nop 0
	global_load_lds_dwordx4 v230, s[48:49]
	s_add_i32 m0, s51, 0xa000
	s_nop 0
	global_load_lds_dwordx4 v229, s[48:49]
	s_add_i32 m0, s51, 0xa400
	s_nop 0
	global_load_lds_dwordx4 v231, s[48:49]
	v_add_u32_e32 v228, 0x80, v228
	v_add_u32_e32 v229, 0x80, v229
	v_add_u32_e32 v230, 0x80, v230
	v_add_u32_e32 v231, 0x80, v231
	s_waitcnt vmcnt(4)
	s_barrier
	s_mov_b32 s52, 0
.Lin2_loop:
	v_add_u32_e32 v234, s22, v232
	v_add_u32_e32 v236, s28, v232
	v_add_u32_e32 v235, s22, v233
	v_add_u32_e32 v237, s28, v233
	ds_read_b128 v[136:139], v234
	ds_read_b128 v[140:143], v234 offset:2048
	ds_read_b128 v[144:147], v234 offset:4096
	ds_read_b128 v[148:151], v234 offset:6144
	ds_read_b128 v[188:191], v236
	ds_read_b128 v[196:199], v236 offset:2048
	ds_read_b128 v[200:203], v236 offset:4096
	ds_read_b128 v[204:207], v236 offset:6144
	ds_read_b128 v[172:175], v235
	ds_read_b128 v[176:179], v235 offset:2048
	ds_read_b128 v[180:183], v235 offset:4096
	ds_read_b128 v[184:187], v235 offset:6144
	ds_read_b128 v[212:215], v237
	ds_read_b128 v[216:219], v237 offset:2048
	ds_read_b128 v[220:223], v237 offset:4096
	ds_read_b128 v[224:227], v237 offset:6144
	s_add_i32 m0, s51, 0xc000
	s_nop 0
	global_load_lds_dwordx4 v228, s[44:45]
	s_add_i32 m0, s51, 0xc400
	s_nop 0
	global_load_lds_dwordx4 v230, s[44:45]
	s_add_i32 m0, s51, 0xe000
	s_nop 0
	global_load_lds_dwordx4 v229, s[44:45]
	s_add_i32 m0, s51, 0xe400
	s_nop 0
	global_load_lds_dwordx4 v231, s[44:45]
	s_add_i32 m0, s51, 0x10000
	s_nop 0
	global_load_lds_dwordx4 v228, s[46:47]
	s_add_i32 m0, s51, 0x10400
	s_nop 0
	global_load_lds_dwordx4 v230, s[46:47]
	s_waitcnt lgkmcnt(8)
	v_mfma_f32_16x16x32_bf16 v[2:5], v[136:139], v[188:191], v[2:5]
	v_mfma_f32_16x16x32_bf16 v[6:9], v[136:139], v[196:199], v[6:9]
	v_mfma_f32_16x16x32_bf16 v[10:13], v[136:139], v[200:203], v[10:13]
	v_mfma_f32_16x16x32_bf16 v[14:17], v[136:139], v[204:207], v[14:17]
	v_mfma_f32_16x16x32_bf16 v[18:21], v[140:143], v[188:191], v[18:21]
	v_mfma_f32_16x16x32_bf16 v[22:25], v[140:143], v[196:199], v[22:25]
	v_mfma_f32_16x16x32_bf16 v[26:29], v[140:143], v[200:203], v[26:29]
	v_mfma_f32_16x16x32_bf16 v[30:33], v[140:143], v[204:207], v[30:33]
	v_mfma_f32_16x16x32_bf16 v[34:37], v[144:147], v[188:191], v[34:37]
	v_mfma_f32_16x16x32_bf16 v[38:41], v[144:147], v[196:199], v[38:41]
	v_mfma_f32_16x16x32_bf16 v[42:45], v[144:147], v[200:203], v[42:45]
	v_mfma_f32_16x16x32_bf16 v[46:49], v[144:147], v[204:207], v[46:49]
	v_mfma_f32_16x16x32_bf16 v[50:53], v[148:151], v[188:191], v[50:53]
	v_mfma_f32_16x16x32_bf16 v[54:57], v[148:151], v[196:199], v[54:57]
	v_mfma_f32_16x16x32_bf16 v[58:61], v[148:151], v[200:203], v[58:61]
	v_mfma_f32_16x16x32_bf16 v[62:65], v[148:151], v[204:207], v[62:65]
	s_waitcnt lgkmcnt(0)
	v_mfma_f32_16x16x32_bf16 v[2:5], v[172:175], v[212:215], v[2:5]
	v_mfma_f32_16x16x32_bf16 v[6:9], v[172:175], v[216:219], v[6:9]
	v_mfma_f32_16x16x32_bf16 v[10:13], v[172:175], v[220:223], v[10:13]
	v_mfma_f32_16x16x32_bf16 v[14:17], v[172:175], v[224:227], v[14:17]
	v_mfma_f32_16x16x32_bf16 v[18:21], v[176:179], v[212:215], v[18:21]
	v_mfma_f32_16x16x32_bf16 v[22:25], v[176:179], v[216:219], v[22:25]
	v_mfma_f32_16x16x32_bf16 v[26:29], v[176:179], v[220:223], v[26:29]
	v_mfma_f32_16x16x32_bf16 v[30:33], v[176:179], v[224:227], v[30:33]
	v_mfma_f32_16x16x32_bf16 v[34:37], v[180:183], v[212:215], v[34:37]
	v_mfma_f32_16x16x32_bf16 v[38:41], v[180:183], v[216:219], v[38:41]
	v_mfma_f32_16x16x32_bf16 v[42:45], v[180:183], v[220:223], v[42:45]
	v_mfma_f32_16x16x32_bf16 v[46:49], v[180:183], v[224:227], v[46:49]
	v_mfma_f32_16x16x32_bf16 v[50:53], v[184:187], v[212:215], v[50:53]
	v_mfma_f32_16x16x32_bf16 v[54:57], v[184:187], v[216:219], v[54:57]
	v_mfma_f32_16x16x32_bf16 v[58:61], v[184:187], v[220:223], v[58:61]
	v_mfma_f32_16x16x32_bf16 v[62:65], v[184:187], v[224:227], v[62:65]
	s_waitcnt vmcnt(6)
	s_barrier
	v_add_u32_e32 v236, s40, v232
	v_add_u32_e32 v237, s40, v233
	ds_read_b128 v[188:191], v236
	ds_read_b128 v[196:199], v236 offset:2048
	ds_read_b128 v[200:203], v236 offset:4096
	ds_read_b128 v[204:207], v236 offset:6144
	ds_read_b128 v[212:215], v237
	ds_read_b128 v[216:219], v237 offset:2048
	ds_read_b128 v[220:223], v237 offset:4096
	ds_read_b128 v[224:227], v237 offset:6144
	s_mov_b32 m0, s51
	s_nop 0
	global_load_lds_dwordx4 v229, s[46:47]
	s_add_i32 m0, s51, 0x400
	s_nop 0
	global_load_lds_dwordx4 v231, s[46:47]
	s_add_i32 m0, s51, 0x2000
	s_nop 0
	global_load_lds_dwordx4 v228, s[48:49]
	s_add_i32 m0, s51, 0x2400
	s_nop 0
	global_load_lds_dwordx4 v230, s[48:49]
	s_add_i32 m0, s51, 0x4000
	s_nop 0
	global_load_lds_dwordx4 v229, s[48:49]
	s_add_i32 m0, s51, 0x4400
	s_nop 0
	global_load_lds_dwordx4 v231, s[48:49]
	s_waitcnt lgkmcnt(4)
	v_mfma_f32_16x16x32_bf16 v[66:69], v[136:139], v[188:191], v[66:69]
	v_mfma_f32_16x16x32_bf16 v[70:73], v[136:139], v[196:199], v[70:73]
	v_mfma_f32_16x16x32_bf16 v[74:77], v[136:139], v[200:203], v[74:77]
	v_mfma_f32_16x16x32_bf16 v[78:81], v[136:139], v[204:207], v[78:81]
	v_mfma_f32_16x16x32_bf16 v[82:85], v[140:143], v[188:191], v[82:85]
	v_mfma_f32_16x16x32_bf16 v[86:89], v[140:143], v[196:199], v[86:89]
	v_mfma_f32_16x16x32_bf16 v[90:93], v[140:143], v[200:203], v[90:93]
	v_mfma_f32_16x16x32_bf16 v[94:97], v[140:143], v[204:207], v[94:97]
	v_mfma_f32_16x16x32_bf16 v[98:101], v[144:147], v[188:191], v[98:101]
	v_mfma_f32_16x16x32_bf16 v[102:105], v[144:147], v[196:199], v[102:105]
	v_mfma_f32_16x16x32_bf16 v[106:109], v[144:147], v[200:203], v[106:109]
	v_mfma_f32_16x16x32_bf16 v[110:113], v[144:147], v[204:207], v[110:113]
	v_mfma_f32_16x16x32_bf16 v[114:117], v[148:151], v[188:191], v[114:117]
	v_mfma_f32_16x16x32_bf16 v[118:121], v[148:151], v[196:199], v[118:121]
	v_mfma_f32_16x16x32_bf16 v[122:125], v[148:151], v[200:203], v[122:125]
	v_mfma_f32_16x16x32_bf16 v[126:129], v[148:151], v[204:207], v[126:129]
	s_waitcnt lgkmcnt(0)
	v_mfma_f32_16x16x32_bf16 v[66:69], v[172:175], v[212:215], v[66:69]
	v_mfma_f32_16x16x32_bf16 v[70:73], v[172:175], v[216:219], v[70:73]
	v_mfma_f32_16x16x32_bf16 v[74:77], v[172:175], v[220:223], v[74:77]
	v_mfma_f32_16x16x32_bf16 v[78:81], v[172:175], v[224:227], v[78:81]
	v_mfma_f32_16x16x32_bf16 v[82:85], v[176:179], v[212:215], v[82:85]
	v_mfma_f32_16x16x32_bf16 v[86:89], v[176:179], v[216:219], v[86:89]
	v_mfma_f32_16x16x32_bf16 v[90:93], v[176:179], v[220:223], v[90:93]
	v_mfma_f32_16x16x32_bf16 v[94:97], v[176:179], v[224:227], v[94:97]
	v_mfma_f32_16x16x32_bf16 v[98:101], v[180:183], v[212:215], v[98:101]
	v_mfma_f32_16x16x32_bf16 v[102:105], v[180:183], v[216:219], v[102:105]
	v_mfma_f32_16x16x32_bf16 v[106:109], v[180:183], v[220:223], v[106:109]
	v_mfma_f32_16x16x32_bf16 v[110:113], v[180:183], v[224:227], v[110:113]
	v_mfma_f32_16x16x32_bf16 v[114:117], v[184:187], v[212:215], v[114:117]
	v_mfma_f32_16x16x32_bf16 v[118:121], v[184:187], v[216:219], v[118:121]
	v_mfma_f32_16x16x32_bf16 v[122:125], v[184:187], v[220:223], v[122:125]
	v_mfma_f32_16x16x32_bf16 v[126:129], v[184:187], v[224:227], v[126:129]
	v_add_u32_e32 v228, 0x80, v228
	v_add_u32_e32 v229, 0x80, v229
	v_add_u32_e32 v230, 0x80, v230
	v_add_u32_e32 v231, 0x80, v231
	s_waitcnt vmcnt(4)
	s_barrier
	v_add_u32_e32 v234, s23, v232
	v_add_u32_e32 v236, s29, v232
	v_add_u32_e32 v235, s23, v233
	v_add_u32_e32 v237, s29, v233
	ds_read_b128 v[136:139], v234
	ds_read_b128 v[140:143], v234 offset:2048
	ds_read_b128 v[144:147], v234 offset:4096
	ds_read_b128 v[148:151], v234 offset:6144
	ds_read_b128 v[188:191], v236
	ds_read_b128 v[196:199], v236 offset:2048
	ds_read_b128 v[200:203], v236 offset:4096
	ds_read_b128 v[204:207], v236 offset:6144
	ds_read_b128 v[172:175], v235
	ds_read_b128 v[176:179], v235 offset:2048
	ds_read_b128 v[180:183], v235 offset:4096
	ds_read_b128 v[184:187], v235 offset:6144
	ds_read_b128 v[212:215], v237
	ds_read_b128 v[216:219], v237 offset:2048
	ds_read_b128 v[220:223], v237 offset:4096
	ds_read_b128 v[224:227], v237 offset:6144
	s_add_i32 m0, s51, 0x6000
	s_nop 0
	global_load_lds_dwordx4 v228, s[44:45]
	s_add_i32 m0, s51, 0x6400
	s_nop 0
	global_load_lds_dwordx4 v230, s[44:45]
	s_add_i32 m0, s51, 0x8000
	s_nop 0
	global_load_lds_dwordx4 v229, s[44:45]
	s_add_i32 m0, s51, 0x8400
	s_nop 0
	global_load_lds_dwordx4 v231, s[44:45]
	s_add_i32 m0, s51, 0xa000
	s_nop 0
	global_load_lds_dwordx4 v228, s[46:47]
	s_add_i32 m0, s51, 0xa400
	s_nop 0
	global_load_lds_dwordx4 v230, s[46:47]
	s_waitcnt lgkmcnt(8)
	v_mfma_f32_16x16x32_bf16 v[2:5], v[136:139], v[188:191], v[2:5]
	v_mfma_f32_16x16x32_bf16 v[6:9], v[136:139], v[196:199], v[6:9]
	v_mfma_f32_16x16x32_bf16 v[10:13], v[136:139], v[200:203], v[10:13]
	v_mfma_f32_16x16x32_bf16 v[14:17], v[136:139], v[204:207], v[14:17]
	v_mfma_f32_16x16x32_bf16 v[18:21], v[140:143], v[188:191], v[18:21]
	v_mfma_f32_16x16x32_bf16 v[22:25], v[140:143], v[196:199], v[22:25]
	v_mfma_f32_16x16x32_bf16 v[26:29], v[140:143], v[200:203], v[26:29]
	v_mfma_f32_16x16x32_bf16 v[30:33], v[140:143], v[204:207], v[30:33]
	v_mfma_f32_16x16x32_bf16 v[34:37], v[144:147], v[188:191], v[34:37]
	v_mfma_f32_16x16x32_bf16 v[38:41], v[144:147], v[196:199], v[38:41]
	v_mfma_f32_16x16x32_bf16 v[42:45], v[144:147], v[200:203], v[42:45]
	v_mfma_f32_16x16x32_bf16 v[46:49], v[144:147], v[204:207], v[46:49]
	v_mfma_f32_16x16x32_bf16 v[50:53], v[148:151], v[188:191], v[50:53]
	v_mfma_f32_16x16x32_bf16 v[54:57], v[148:151], v[196:199], v[54:57]
	v_mfma_f32_16x16x32_bf16 v[58:61], v[148:151], v[200:203], v[58:61]
	v_mfma_f32_16x16x32_bf16 v[62:65], v[148:151], v[204:207], v[62:65]
	s_waitcnt lgkmcnt(0)
	v_mfma_f32_16x16x32_bf16 v[2:5], v[172:175], v[212:215], v[2:5]
	v_mfma_f32_16x16x32_bf16 v[6:9], v[172:175], v[216:219], v[6:9]
	v_mfma_f32_16x16x32_bf16 v[10:13], v[172:175], v[220:223], v[10:13]
	v_mfma_f32_16x16x32_bf16 v[14:17], v[172:175], v[224:227], v[14:17]
	v_mfma_f32_16x16x32_bf16 v[18:21], v[176:179], v[212:215], v[18:21]
	v_mfma_f32_16x16x32_bf16 v[22:25], v[176:179], v[216:219], v[22:25]
	v_mfma_f32_16x16x32_bf16 v[26:29], v[176:179], v[220:223], v[26:29]
	v_mfma_f32_16x16x32_bf16 v[30:33], v[176:179], v[224:227], v[30:33]
	v_mfma_f32_16x16x32_bf16 v[34:37], v[180:183], v[212:215], v[34:37]
	v_mfma_f32_16x16x32_bf16 v[38:41], v[180:183], v[216:219], v[38:41]
	v_mfma_f32_16x16x32_bf16 v[42:45], v[180:183], v[220:223], v[42:45]
	v_mfma_f32_16x16x32_bf16 v[46:49], v[180:183], v[224:227], v[46:49]
	v_mfma_f32_16x16x32_bf16 v[50:53], v[184:187], v[212:215], v[50:53]
	v_mfma_f32_16x16x32_bf16 v[54:57], v[184:187], v[216:219], v[54:57]
	v_mfma_f32_16x16x32_bf16 v[58:61], v[184:187], v[220:223], v[58:61]
	v_mfma_f32_16x16x32_bf16 v[62:65], v[184:187], v[224:227], v[62:65]
	s_waitcnt vmcnt(6)
	s_barrier
	v_add_u32_e32 v236, s41, v232
	v_add_u32_e32 v237, s41, v233
	ds_read_b128 v[188:191], v236
	ds_read_b128 v[196:199], v236 offset:2048
	ds_read_b128 v[200:203], v236 offset:4096
	ds_read_b128 v[204:207], v236 offset:6144
	ds_read_b128 v[212:215], v237
	ds_read_b128 v[216:219], v237 offset:2048
	ds_read_b128 v[220:223], v237 offset:4096
	ds_read_b128 v[224:227], v237 offset:6144
	s_add_i32 m0, s51, 0xc000
	s_nop 0
	global_load_lds_dwordx4 v229, s[46:47]
	s_add_i32 m0, s51, 0xc400
	s_nop 0
	global_load_lds_dwordx4 v231, s[46:47]
	s_add_i32 m0, s51, 0xe000
	s_nop 0
	global_load_lds_dwordx4 v228, s[48:49]
	s_add_i32 m0, s51, 0xe400
	s_nop 0
	global_load_lds_dwordx4 v230, s[48:49]
	s_add_i32 m0, s51, 0x10000
	s_nop 0
	global_load_lds_dwordx4 v229, s[48:49]
	s_add_i32 m0, s51, 0x10400
	s_nop 0
	global_load_lds_dwordx4 v231, s[48:49]
	s_waitcnt lgkmcnt(4)
	v_mfma_f32_16x16x32_bf16 v[66:69], v[136:139], v[188:191], v[66:69]
	v_mfma_f32_16x16x32_bf16 v[70:73], v[136:139], v[196:199], v[70:73]
	v_mfma_f32_16x16x32_bf16 v[74:77], v[136:139], v[200:203], v[74:77]
	v_mfma_f32_16x16x32_bf16 v[78:81], v[136:139], v[204:207], v[78:81]
	v_mfma_f32_16x16x32_bf16 v[82:85], v[140:143], v[188:191], v[82:85]
	v_mfma_f32_16x16x32_bf16 v[86:89], v[140:143], v[196:199], v[86:89]
	v_mfma_f32_16x16x32_bf16 v[90:93], v[140:143], v[200:203], v[90:93]
	v_mfma_f32_16x16x32_bf16 v[94:97], v[140:143], v[204:207], v[94:97]
	v_mfma_f32_16x16x32_bf16 v[98:101], v[144:147], v[188:191], v[98:101]
	v_mfma_f32_16x16x32_bf16 v[102:105], v[144:147], v[196:199], v[102:105]
	v_mfma_f32_16x16x32_bf16 v[106:109], v[144:147], v[200:203], v[106:109]
	v_mfma_f32_16x16x32_bf16 v[110:113], v[144:147], v[204:207], v[110:113]
	v_mfma_f32_16x16x32_bf16 v[114:117], v[148:151], v[188:191], v[114:117]
	v_mfma_f32_16x16x32_bf16 v[118:121], v[148:151], v[196:199], v[118:121]
	v_mfma_f32_16x16x32_bf16 v[122:125], v[148:151], v[200:203], v[122:125]
	v_mfma_f32_16x16x32_bf16 v[126:129], v[148:151], v[204:207], v[126:129]
	s_waitcnt lgkmcnt(0)
	v_mfma_f32_16x16x32_bf16 v[66:69], v[172:175], v[212:215], v[66:69]
	v_mfma_f32_16x16x32_bf16 v[70:73], v[172:175], v[216:219], v[70:73]
	v_mfma_f32_16x16x32_bf16 v[74:77], v[172:175], v[220:223], v[74:77]
	v_mfma_f32_16x16x32_bf16 v[78:81], v[172:175], v[224:227], v[78:81]
	v_mfma_f32_16x16x32_bf16 v[82:85], v[176:179], v[212:215], v[82:85]
	v_mfma_f32_16x16x32_bf16 v[86:89], v[176:179], v[216:219], v[86:89]
	v_mfma_f32_16x16x32_bf16 v[90:93], v[176:179], v[220:223], v[90:93]
	v_mfma_f32_16x16x32_bf16 v[94:97], v[176:179], v[224:227], v[94:97]
	v_mfma_f32_16x16x32_bf16 v[98:101], v[180:183], v[212:215], v[98:101]
	v_mfma_f32_16x16x32_bf16 v[102:105], v[180:183], v[216:219], v[102:105]
	v_mfma_f32_16x16x32_bf16 v[106:109], v[180:183], v[220:223], v[106:109]
	v_mfma_f32_16x16x32_bf16 v[110:113], v[180:183], v[224:227], v[110:113]
	v_mfma_f32_16x16x32_bf16 v[114:117], v[184:187], v[212:215], v[114:117]
	v_mfma_f32_16x16x32_bf16 v[118:121], v[184:187], v[216:219], v[118:121]
	v_mfma_f32_16x16x32_bf16 v[122:125], v[184:187], v[220:223], v[122:125]
	v_mfma_f32_16x16x32_bf16 v[126:129], v[184:187], v[224:227], v[126:129]
	v_add_u32_e32 v228, 0x80, v228
	v_add_u32_e32 v229, 0x80, v229
	v_add_u32_e32 v230, 0x80, v230
	v_add_u32_e32 v231, 0x80, v231
	s_waitcnt vmcnt(4)
	s_barrier
	v_add_u32_e32 v234, s24, v232
	v_add_u32_e32 v236, s30, v232
	v_add_u32_e32 v235, s24, v233
	v_add_u32_e32 v237, s30, v233
	ds_read_b128 v[136:139], v234
	ds_read_b128 v[140:143], v234 offset:2048
	ds_read_b128 v[144:147], v234 offset:4096
	ds_read_b128 v[148:151], v234 offset:6144
	ds_read_b128 v[188:191], v236
	ds_read_b128 v[196:199], v236 offset:2048
	ds_read_b128 v[200:203], v236 offset:4096
	ds_read_b128 v[204:207], v236 offset:6144
	ds_read_b128 v[172:175], v235
	ds_read_b128 v[176:179], v235 offset:2048
	ds_read_b128 v[180:183], v235 offset:4096
	ds_read_b128 v[184:187], v235 offset:6144
	ds_read_b128 v[212:215], v237
	ds_read_b128 v[216:219], v237 offset:2048
	ds_read_b128 v[220:223], v237 offset:4096
	ds_read_b128 v[224:227], v237 offset:6144
	s_mov_b32 m0, s51
	s_nop 0
	global_load_lds_dwordx4 v228, s[44:45]
	s_add_i32 m0, s51, 0x400
	s_nop 0
	global_load_lds_dwordx4 v230, s[44:45]
	s_add_i32 m0, s51, 0x2000
	s_nop 0
	global_load_lds_dwordx4 v229, s[44:45]
	s_add_i32 m0, s51, 0x2400
	s_nop 0
	global_load_lds_dwordx4 v231, s[44:45]
	s_add_i32 m0, s51, 0x4000
	s_nop 0
	global_load_lds_dwordx4 v228, s[46:47]
	s_add_i32 m0, s51, 0x4400
	s_nop 0
	global_load_lds_dwordx4 v230, s[46:47]
	s_waitcnt lgkmcnt(8)
	v_mfma_f32_16x16x32_bf16 v[2:5], v[136:139], v[188:191], v[2:5]
	v_mfma_f32_16x16x32_bf16 v[6:9], v[136:139], v[196:199], v[6:9]
	v_mfma_f32_16x16x32_bf16 v[10:13], v[136:139], v[200:203], v[10:13]
	v_mfma_f32_16x16x32_bf16 v[14:17], v[136:139], v[204:207], v[14:17]
	v_mfma_f32_16x16x32_bf16 v[18:21], v[140:143], v[188:191], v[18:21]
	v_mfma_f32_16x16x32_bf16 v[22:25], v[140:143], v[196:199], v[22:25]
	v_mfma_f32_16x16x32_bf16 v[26:29], v[140:143], v[200:203], v[26:29]
	v_mfma_f32_16x16x32_bf16 v[30:33], v[140:143], v[204:207], v[30:33]
	v_mfma_f32_16x16x32_bf16 v[34:37], v[144:147], v[188:191], v[34:37]
	v_mfma_f32_16x16x32_bf16 v[38:41], v[144:147], v[196:199], v[38:41]
	v_mfma_f32_16x16x32_bf16 v[42:45], v[144:147], v[200:203], v[42:45]
	v_mfma_f32_16x16x32_bf16 v[46:49], v[144:147], v[204:207], v[46:49]
	v_mfma_f32_16x16x32_bf16 v[50:53], v[148:151], v[188:191], v[50:53]
	v_mfma_f32_16x16x32_bf16 v[54:57], v[148:151], v[196:199], v[54:57]
	v_mfma_f32_16x16x32_bf16 v[58:61], v[148:151], v[200:203], v[58:61]
	v_mfma_f32_16x16x32_bf16 v[62:65], v[148:151], v[204:207], v[62:65]
	s_waitcnt lgkmcnt(0)
	v_mfma_f32_16x16x32_bf16 v[2:5], v[172:175], v[212:215], v[2:5]
	v_mfma_f32_16x16x32_bf16 v[6:9], v[172:175], v[216:219], v[6:9]
	v_mfma_f32_16x16x32_bf16 v[10:13], v[172:175], v[220:223], v[10:13]
	v_mfma_f32_16x16x32_bf16 v[14:17], v[172:175], v[224:227], v[14:17]
	v_mfma_f32_16x16x32_bf16 v[18:21], v[176:179], v[212:215], v[18:21]
	v_mfma_f32_16x16x32_bf16 v[22:25], v[176:179], v[216:219], v[22:25]
	v_mfma_f32_16x16x32_bf16 v[26:29], v[176:179], v[220:223], v[26:29]
	v_mfma_f32_16x16x32_bf16 v[30:33], v[176:179], v[224:227], v[30:33]
	v_mfma_f32_16x16x32_bf16 v[34:37], v[180:183], v[212:215], v[34:37]
	v_mfma_f32_16x16x32_bf16 v[38:41], v[180:183], v[216:219], v[38:41]
	v_mfma_f32_16x16x32_bf16 v[42:45], v[180:183], v[220:223], v[42:45]
	v_mfma_f32_16x16x32_bf16 v[46:49], v[180:183], v[224:227], v[46:49]
	v_mfma_f32_16x16x32_bf16 v[50:53], v[184:187], v[212:215], v[50:53]
	v_mfma_f32_16x16x32_bf16 v[54:57], v[184:187], v[216:219], v[54:57]
	v_mfma_f32_16x16x32_bf16 v[58:61], v[184:187], v[220:223], v[58:61]
	v_mfma_f32_16x16x32_bf16 v[62:65], v[184:187], v[224:227], v[62:65]
	s_waitcnt vmcnt(6)
	s_barrier
	v_add_u32_e32 v236, s42, v232
	v_add_u32_e32 v237, s42, v233
	ds_read_b128 v[188:191], v236
	ds_read_b128 v[196:199], v236 offset:2048
	ds_read_b128 v[200:203], v236 offset:4096
	ds_read_b128 v[204:207], v236 offset:6144
	ds_read_b128 v[212:215], v237
	ds_read_b128 v[216:219], v237 offset:2048
	ds_read_b128 v[220:223], v237 offset:4096
	ds_read_b128 v[224:227], v237 offset:6144
	s_add_i32 m0, s51, 0x6000
	s_nop 0
	global_load_lds_dwordx4 v229, s[46:47]
	s_add_i32 m0, s51, 0x6400
	s_nop 0
	global_load_lds_dwordx4 v231, s[46:47]
	s_add_i32 m0, s51, 0x8000
	s_nop 0
	global_load_lds_dwordx4 v228, s[48:49]
	s_add_i32 m0, s51, 0x8400
	s_nop 0
	global_load_lds_dwordx4 v230, s[48:49]
	s_add_i32 m0, s51, 0xa000
	s_nop 0
	global_load_lds_dwordx4 v229, s[48:49]
	s_add_i32 m0, s51, 0xa400
	s_nop 0
	global_load_lds_dwordx4 v231, s[48:49]
	s_waitcnt lgkmcnt(4)
	v_mfma_f32_16x16x32_bf16 v[66:69], v[136:139], v[188:191], v[66:69]
	v_mfma_f32_16x16x32_bf16 v[70:73], v[136:139], v[196:199], v[70:73]
	v_mfma_f32_16x16x32_bf16 v[74:77], v[136:139], v[200:203], v[74:77]
	v_mfma_f32_16x16x32_bf16 v[78:81], v[136:139], v[204:207], v[78:81]
	v_mfma_f32_16x16x32_bf16 v[82:85], v[140:143], v[188:191], v[82:85]
	v_mfma_f32_16x16x32_bf16 v[86:89], v[140:143], v[196:199], v[86:89]
	v_mfma_f32_16x16x32_bf16 v[90:93], v[140:143], v[200:203], v[90:93]
	v_mfma_f32_16x16x32_bf16 v[94:97], v[140:143], v[204:207], v[94:97]
	v_mfma_f32_16x16x32_bf16 v[98:101], v[144:147], v[188:191], v[98:101]
	v_mfma_f32_16x16x32_bf16 v[102:105], v[144:147], v[196:199], v[102:105]
	v_mfma_f32_16x16x32_bf16 v[106:109], v[144:147], v[200:203], v[106:109]
	v_mfma_f32_16x16x32_bf16 v[110:113], v[144:147], v[204:207], v[110:113]
	v_mfma_f32_16x16x32_bf16 v[114:117], v[148:151], v[188:191], v[114:117]
	v_mfma_f32_16x16x32_bf16 v[118:121], v[148:151], v[196:199], v[118:121]
	v_mfma_f32_16x16x32_bf16 v[122:125], v[148:151], v[200:203], v[122:125]
	v_mfma_f32_16x16x32_bf16 v[126:129], v[148:151], v[204:207], v[126:129]
	s_waitcnt lgkmcnt(0)
	v_mfma_f32_16x16x32_bf16 v[66:69], v[172:175], v[212:215], v[66:69]
	v_mfma_f32_16x16x32_bf16 v[70:73], v[172:175], v[216:219], v[70:73]
	v_mfma_f32_16x16x32_bf16 v[74:77], v[172:175], v[220:223], v[74:77]
	v_mfma_f32_16x16x32_bf16 v[78:81], v[172:175], v[224:227], v[78:81]
	v_mfma_f32_16x16x32_bf16 v[82:85], v[176:179], v[212:215], v[82:85]
	v_mfma_f32_16x16x32_bf16 v[86:89], v[176:179], v[216:219], v[86:89]
	v_mfma_f32_16x16x32_bf16 v[90:93], v[176:179], v[220:223], v[90:93]
	v_mfma_f32_16x16x32_bf16 v[94:97], v[176:179], v[224:227], v[94:97]
	v_mfma_f32_16x16x32_bf16 v[98:101], v[180:183], v[212:215], v[98:101]
	v_mfma_f32_16x16x32_bf16 v[102:105], v[180:183], v[216:219], v[102:105]
	v_mfma_f32_16x16x32_bf16 v[106:109], v[180:183], v[220:223], v[106:109]
	v_mfma_f32_16x16x32_bf16 v[110:113], v[180:183], v[224:227], v[110:113]
	v_mfma_f32_16x16x32_bf16 v[114:117], v[184:187], v[212:215], v[114:117]
	v_mfma_f32_16x16x32_bf16 v[118:121], v[184:187], v[216:219], v[118:121]
	v_mfma_f32_16x16x32_bf16 v[122:125], v[184:187], v[220:223], v[122:125]
	v_mfma_f32_16x16x32_bf16 v[126:129], v[184:187], v[224:227], v[126:129]
	v_add_u32_e32 v228, 0x80, v228
	v_add_u32_e32 v229, 0x80, v229
	v_add_u32_e32 v230, 0x80, v230
	v_add_u32_e32 v231, 0x80, v231
	s_waitcnt vmcnt(4)
	s_barrier
	s_add_i32 s52, s52, 1
	s_cmp_lt_u32 s52, 10
	s_cbranch_scc1 .Lin2_loop
	v_add_u32_e32 v234, s22, v232
	v_add_u32_e32 v236, s28, v232
	v_add_u32_e32 v235, s22, v233
	v_add_u32_e32 v237, s28, v233
	ds_read_b128 v[136:139], v234
	ds_read_b128 v[140:143], v234 offset:2048
	ds_read_b128 v[144:147], v234 offset:4096
	ds_read_b128 v[148:151], v234 offset:6144
	ds_read_b128 v[188:191], v236
	ds_read_b128 v[196:199], v236 offset:2048
	ds_read_b128 v[200:203], v236 offset:4096
	ds_read_b128 v[204:207], v236 offset:6144
	ds_read_b128 v[172:175], v235
	ds_read_b128 v[176:179], v235 offset:2048
	ds_read_b128 v[180:183], v235 offset:4096
	ds_read_b128 v[184:187], v235 offset:6144
	ds_read_b128 v[212:215], v237
	ds_read_b128 v[216:219], v237 offset:2048
	ds_read_b128 v[220:223], v237 offset:4096
	ds_read_b128 v[224:227], v237 offset:6144
	s_add_i32 m0, s51, 0xc000
	s_nop 0
	global_load_lds_dwordx4 v228, s[44:45]
	s_add_i32 m0, s51, 0xc400
	s_nop 0
	global_load_lds_dwordx4 v230, s[44:45]
	s_add_i32 m0, s51, 0xe000
	s_nop 0
	global_load_lds_dwordx4 v229, s[44:45]
	s_add_i32 m0, s51, 0xe400
	s_nop 0
	global_load_lds_dwordx4 v231, s[44:45]
	s_add_i32 m0, s51, 0x10000
	s_nop 0
	global_load_lds_dwordx4 v228, s[46:47]
	s_add_i32 m0, s51, 0x10400
	s_nop 0
	global_load_lds_dwordx4 v230, s[46:47]
	s_waitcnt lgkmcnt(8)
	v_mfma_f32_16x16x32_bf16 v[2:5], v[136:139], v[188:191], v[2:5]
	v_mfma_f32_16x16x32_bf16 v[6:9], v[136:139], v[196:199], v[6:9]
	v_mfma_f32_16x16x32_bf16 v[10:13], v[136:139], v[200:203], v[10:13]
	v_mfma_f32_16x16x32_bf16 v[14:17], v[136:139], v[204:207], v[14:17]
	v_mfma_f32_16x16x32_bf16 v[18:21], v[140:143], v[188:191], v[18:21]
	v_mfma_f32_16x16x32_bf16 v[22:25], v[140:143], v[196:199], v[22:25]
	v_mfma_f32_16x16x32_bf16 v[26:29], v[140:143], v[200:203], v[26:29]
	v_mfma_f32_16x16x32_bf16 v[30:33], v[140:143], v[204:207], v[30:33]
	v_mfma_f32_16x16x32_bf16 v[34:37], v[144:147], v[188:191], v[34:37]
	v_mfma_f32_16x16x32_bf16 v[38:41], v[144:147], v[196:199], v[38:41]
	v_mfma_f32_16x16x32_bf16 v[42:45], v[144:147], v[200:203], v[42:45]
	v_mfma_f32_16x16x32_bf16 v[46:49], v[144:147], v[204:207], v[46:49]
	v_mfma_f32_16x16x32_bf16 v[50:53], v[148:151], v[188:191], v[50:53]
	v_mfma_f32_16x16x32_bf16 v[54:57], v[148:151], v[196:199], v[54:57]
	v_mfma_f32_16x16x32_bf16 v[58:61], v[148:151], v[200:203], v[58:61]
	v_mfma_f32_16x16x32_bf16 v[62:65], v[148:151], v[204:207], v[62:65]
	s_waitcnt lgkmcnt(0)
	v_mfma_f32_16x16x32_bf16 v[2:5], v[172:175], v[212:215], v[2:5]
	v_mfma_f32_16x16x32_bf16 v[6:9], v[172:175], v[216:219], v[6:9]
	v_mfma_f32_16x16x32_bf16 v[10:13], v[172:175], v[220:223], v[10:13]
	v_mfma_f32_16x16x32_bf16 v[14:17], v[172:175], v[224:227], v[14:17]
	v_mfma_f32_16x16x32_bf16 v[18:21], v[176:179], v[212:215], v[18:21]
	v_mfma_f32_16x16x32_bf16 v[22:25], v[176:179], v[216:219], v[22:25]
	v_mfma_f32_16x16x32_bf16 v[26:29], v[176:179], v[220:223], v[26:29]
	v_mfma_f32_16x16x32_bf16 v[30:33], v[176:179], v[224:227], v[30:33]
	v_mfma_f32_16x16x32_bf16 v[34:37], v[180:183], v[212:215], v[34:37]
	v_mfma_f32_16x16x32_bf16 v[38:41], v[180:183], v[216:219], v[38:41]
	v_mfma_f32_16x16x32_bf16 v[42:45], v[180:183], v[220:223], v[42:45]
	v_mfma_f32_16x16x32_bf16 v[46:49], v[180:183], v[224:227], v[46:49]
	v_mfma_f32_16x16x32_bf16 v[50:53], v[184:187], v[212:215], v[50:53]
	v_mfma_f32_16x16x32_bf16 v[54:57], v[184:187], v[216:219], v[54:57]
	v_mfma_f32_16x16x32_bf16 v[58:61], v[184:187], v[220:223], v[58:61]
	v_mfma_f32_16x16x32_bf16 v[62:65], v[184:187], v[224:227], v[62:65]
	s_waitcnt vmcnt(6)
	s_barrier
	v_add_u32_e32 v236, s40, v232
	v_add_u32_e32 v237, s40, v233
	ds_read_b128 v[188:191], v236
	ds_read_b128 v[196:199], v236 offset:2048
	ds_read_b128 v[200:203], v236 offset:4096
	ds_read_b128 v[204:207], v236 offset:6144
	ds_read_b128 v[212:215], v237
	ds_read_b128 v[216:219], v237 offset:2048
	ds_read_b128 v[220:223], v237 offset:4096
	ds_read_b128 v[224:227], v237 offset:6144
	s_mov_b32 m0, s51
	s_nop 0
	global_load_lds_dwordx4 v229, s[46:47]
	s_add_i32 m0, s51, 0x400
	s_nop 0
	global_load_lds_dwordx4 v231, s[46:47]
	s_add_i32 m0, s51, 0x2000
	s_nop 0
	global_load_lds_dwordx4 v228, s[48:49]
	s_add_i32 m0, s51, 0x2400
	s_nop 0
	global_load_lds_dwordx4 v230, s[48:49]
	s_add_i32 m0, s51, 0x4000
	s_nop 0
	global_load_lds_dwordx4 v229, s[48:49]
	s_add_i32 m0, s51, 0x4400
	s_nop 0
	global_load_lds_dwordx4 v231, s[48:49]
	s_waitcnt lgkmcnt(4)
	v_mfma_f32_16x16x32_bf16 v[66:69], v[136:139], v[188:191], v[66:69]
	v_mfma_f32_16x16x32_bf16 v[70:73], v[136:139], v[196:199], v[70:73]
	v_mfma_f32_16x16x32_bf16 v[74:77], v[136:139], v[200:203], v[74:77]
	v_mfma_f32_16x16x32_bf16 v[78:81], v[136:139], v[204:207], v[78:81]
	v_mfma_f32_16x16x32_bf16 v[82:85], v[140:143], v[188:191], v[82:85]
	v_mfma_f32_16x16x32_bf16 v[86:89], v[140:143], v[196:199], v[86:89]
	v_mfma_f32_16x16x32_bf16 v[90:93], v[140:143], v[200:203], v[90:93]
	v_mfma_f32_16x16x32_bf16 v[94:97], v[140:143], v[204:207], v[94:97]
	v_mfma_f32_16x16x32_bf16 v[98:101], v[144:147], v[188:191], v[98:101]
	v_mfma_f32_16x16x32_bf16 v[102:105], v[144:147], v[196:199], v[102:105]
	v_mfma_f32_16x16x32_bf16 v[106:109], v[144:147], v[200:203], v[106:109]
	v_mfma_f32_16x16x32_bf16 v[110:113], v[144:147], v[204:207], v[110:113]
	v_mfma_f32_16x16x32_bf16 v[114:117], v[148:151], v[188:191], v[114:117]
	v_mfma_f32_16x16x32_bf16 v[118:121], v[148:151], v[196:199], v[118:121]
	v_mfma_f32_16x16x32_bf16 v[122:125], v[148:151], v[200:203], v[122:125]
	v_mfma_f32_16x16x32_bf16 v[126:129], v[148:151], v[204:207], v[126:129]
	s_waitcnt lgkmcnt(0)
	v_mfma_f32_16x16x32_bf16 v[66:69], v[172:175], v[212:215], v[66:69]
	v_mfma_f32_16x16x32_bf16 v[70:73], v[172:175], v[216:219], v[70:73]
	v_mfma_f32_16x16x32_bf16 v[74:77], v[172:175], v[220:223], v[74:77]
	v_mfma_f32_16x16x32_bf16 v[78:81], v[172:175], v[224:227], v[78:81]
	v_mfma_f32_16x16x32_bf16 v[82:85], v[176:179], v[212:215], v[82:85]
	v_mfma_f32_16x16x32_bf16 v[86:89], v[176:179], v[216:219], v[86:89]
	v_mfma_f32_16x16x32_bf16 v[90:93], v[176:179], v[220:223], v[90:93]
	v_mfma_f32_16x16x32_bf16 v[94:97], v[176:179], v[224:227], v[94:97]
	v_mfma_f32_16x16x32_bf16 v[98:101], v[180:183], v[212:215], v[98:101]
	v_mfma_f32_16x16x32_bf16 v[102:105], v[180:183], v[216:219], v[102:105]
	v_mfma_f32_16x16x32_bf16 v[106:109], v[180:183], v[220:223], v[106:109]
	v_mfma_f32_16x16x32_bf16 v[110:113], v[180:183], v[224:227], v[110:113]
	v_mfma_f32_16x16x32_bf16 v[114:117], v[184:187], v[212:215], v[114:117]
	v_mfma_f32_16x16x32_bf16 v[118:121], v[184:187], v[216:219], v[118:121]
	v_mfma_f32_16x16x32_bf16 v[122:125], v[184:187], v[220:223], v[122:125]
	v_mfma_f32_16x16x32_bf16 v[126:129], v[184:187], v[224:227], v[126:129]
	v_add_u32_e32 v228, 0x80, v228
	v_add_u32_e32 v229, 0x80, v229
	v_add_u32_e32 v230, 0x80, v230
	v_add_u32_e32 v231, 0x80, v231
	s_waitcnt vmcnt(4)
	s_barrier
	v_add_u32_e32 v234, s23, v232
	v_add_u32_e32 v236, s29, v232
	v_add_u32_e32 v235, s23, v233
	v_add_u32_e32 v237, s29, v233
	ds_read_b128 v[136:139], v234
	ds_read_b128 v[140:143], v234 offset:2048
	ds_read_b128 v[144:147], v234 offset:4096
	ds_read_b128 v[148:151], v234 offset:6144
	ds_read_b128 v[188:191], v236
	ds_read_b128 v[196:199], v236 offset:2048
	ds_read_b128 v[200:203], v236 offset:4096
	ds_read_b128 v[204:207], v236 offset:6144
	ds_read_b128 v[172:175], v235
	ds_read_b128 v[176:179], v235 offset:2048
	ds_read_b128 v[180:183], v235 offset:4096
	ds_read_b128 v[184:187], v235 offset:6144
	ds_read_b128 v[212:215], v237
	ds_read_b128 v[216:219], v237 offset:2048
	ds_read_b128 v[220:223], v237 offset:4096
	ds_read_b128 v[224:227], v237 offset:6144
	s_waitcnt lgkmcnt(8)
	v_mfma_f32_16x16x32_bf16 v[2:5], v[136:139], v[188:191], v[2:5]
	v_mfma_f32_16x16x32_bf16 v[6:9], v[136:139], v[196:199], v[6:9]
	v_mfma_f32_16x16x32_bf16 v[10:13], v[136:139], v[200:203], v[10:13]
	v_mfma_f32_16x16x32_bf16 v[14:17], v[136:139], v[204:207], v[14:17]
	v_mfma_f32_16x16x32_bf16 v[18:21], v[140:143], v[188:191], v[18:21]
	v_mfma_f32_16x16x32_bf16 v[22:25], v[140:143], v[196:199], v[22:25]
	v_mfma_f32_16x16x32_bf16 v[26:29], v[140:143], v[200:203], v[26:29]
	v_mfma_f32_16x16x32_bf16 v[30:33], v[140:143], v[204:207], v[30:33]
	v_mfma_f32_16x16x32_bf16 v[34:37], v[144:147], v[188:191], v[34:37]
	v_mfma_f32_16x16x32_bf16 v[38:41], v[144:147], v[196:199], v[38:41]
	v_mfma_f32_16x16x32_bf16 v[42:45], v[144:147], v[200:203], v[42:45]
	v_mfma_f32_16x16x32_bf16 v[46:49], v[144:147], v[204:207], v[46:49]
	v_mfma_f32_16x16x32_bf16 v[50:53], v[148:151], v[188:191], v[50:53]
	v_mfma_f32_16x16x32_bf16 v[54:57], v[148:151], v[196:199], v[54:57]
	v_mfma_f32_16x16x32_bf16 v[58:61], v[148:151], v[200:203], v[58:61]
	v_mfma_f32_16x16x32_bf16 v[62:65], v[148:151], v[204:207], v[62:65]
	s_waitcnt lgkmcnt(0)
	v_mfma_f32_16x16x32_bf16 v[2:5], v[172:175], v[212:215], v[2:5]
	v_mfma_f32_16x16x32_bf16 v[6:9], v[172:175], v[216:219], v[6:9]
	v_mfma_f32_16x16x32_bf16 v[10:13], v[172:175], v[220:223], v[10:13]
	v_mfma_f32_16x16x32_bf16 v[14:17], v[172:175], v[224:227], v[14:17]
	v_mfma_f32_16x16x32_bf16 v[18:21], v[176:179], v[212:215], v[18:21]
	v_mfma_f32_16x16x32_bf16 v[22:25], v[176:179], v[216:219], v[22:25]
	v_mfma_f32_16x16x32_bf16 v[26:29], v[176:179], v[220:223], v[26:29]
	v_mfma_f32_16x16x32_bf16 v[30:33], v[176:179], v[224:227], v[30:33]
	v_mfma_f32_16x16x32_bf16 v[34:37], v[180:183], v[212:215], v[34:37]
	v_mfma_f32_16x16x32_bf16 v[38:41], v[180:183], v[216:219], v[38:41]
	v_mfma_f32_16x16x32_bf16 v[42:45], v[180:183], v[220:223], v[42:45]
	v_mfma_f32_16x16x32_bf16 v[46:49], v[180:183], v[224:227], v[46:49]
	v_mfma_f32_16x16x32_bf16 v[50:53], v[184:187], v[212:215], v[50:53]
	v_mfma_f32_16x16x32_bf16 v[54:57], v[184:187], v[216:219], v[54:57]
	v_mfma_f32_16x16x32_bf16 v[58:61], v[184:187], v[220:223], v[58:61]
	v_mfma_f32_16x16x32_bf16 v[62:65], v[184:187], v[224:227], v[62:65]
	s_waitcnt vmcnt(0)
	s_barrier
	v_add_u32_e32 v236, s41, v232
	v_add_u32_e32 v237, s41, v233
	ds_read_b128 v[188:191], v236
	ds_read_b128 v[196:199], v236 offset:2048
	ds_read_b128 v[200:203], v236 offset:4096
	ds_read_b128 v[204:207], v236 offset:6144
	ds_read_b128 v[212:215], v237
	ds_read_b128 v[216:219], v237 offset:2048
	ds_read_b128 v[220:223], v237 offset:4096
	ds_read_b128 v[224:227], v237 offset:6144
	s_waitcnt lgkmcnt(4)
	v_mfma_f32_16x16x32_bf16 v[66:69], v[136:139], v[188:191], v[66:69]
	v_mfma_f32_16x16x32_bf16 v[70:73], v[136:139], v[196:199], v[70:73]
	v_mfma_f32_16x16x32_bf16 v[74:77], v[136:139], v[200:203], v[74:77]
	v_mfma_f32_16x16x32_bf16 v[78:81], v[136:139], v[204:207], v[78:81]
	v_mfma_f32_16x16x32_bf16 v[82:85], v[140:143], v[188:191], v[82:85]
	v_mfma_f32_16x16x32_bf16 v[86:89], v[140:143], v[196:199], v[86:89]
	v_mfma_f32_16x16x32_bf16 v[90:93], v[140:143], v[200:203], v[90:93]
	v_mfma_f32_16x16x32_bf16 v[94:97], v[140:143], v[204:207], v[94:97]
	v_mfma_f32_16x16x32_bf16 v[98:101], v[144:147], v[188:191], v[98:101]
	v_mfma_f32_16x16x32_bf16 v[102:105], v[144:147], v[196:199], v[102:105]
	v_mfma_f32_16x16x32_bf16 v[106:109], v[144:147], v[200:203], v[106:109]
	v_mfma_f32_16x16x32_bf16 v[110:113], v[144:147], v[204:207], v[110:113]
	v_mfma_f32_16x16x32_bf16 v[114:117], v[148:151], v[188:191], v[114:117]
	v_mfma_f32_16x16x32_bf16 v[118:121], v[148:151], v[196:199], v[118:121]
	v_mfma_f32_16x16x32_bf16 v[122:125], v[148:151], v[200:203], v[122:125]
	v_mfma_f32_16x16x32_bf16 v[126:129], v[148:151], v[204:207], v[126:129]
	s_waitcnt lgkmcnt(0)
	v_mfma_f32_16x16x32_bf16 v[66:69], v[172:175], v[212:215], v[66:69]
	v_mfma_f32_16x16x32_bf16 v[70:73], v[172:175], v[216:219], v[70:73]
	v_mfma_f32_16x16x32_bf16 v[74:77], v[172:175], v[220:223], v[74:77]
	v_mfma_f32_16x16x32_bf16 v[78:81], v[172:175], v[224:227], v[78:81]
	v_mfma_f32_16x16x32_bf16 v[82:85], v[176:179], v[212:215], v[82:85]
	v_mfma_f32_16x16x32_bf16 v[86:89], v[176:179], v[216:219], v[86:89]
	v_mfma_f32_16x16x32_bf16 v[90:93], v[176:179], v[220:223], v[90:93]
	v_mfma_f32_16x16x32_bf16 v[94:97], v[176:179], v[224:227], v[94:97]
	v_mfma_f32_16x16x32_bf16 v[98:101], v[180:183], v[212:215], v[98:101]
	v_mfma_f32_16x16x32_bf16 v[102:105], v[180:183], v[216:219], v[102:105]
	v_mfma_f32_16x16x32_bf16 v[106:109], v[180:183], v[220:223], v[106:109]
	v_mfma_f32_16x16x32_bf16 v[110:113], v[180:183], v[224:227], v[110:113]
	v_mfma_f32_16x16x32_bf16 v[114:117], v[184:187], v[212:215], v[114:117]
	v_mfma_f32_16x16x32_bf16 v[118:121], v[184:187], v[216:219], v[118:121]
	v_mfma_f32_16x16x32_bf16 v[122:125], v[184:187], v[220:223], v[122:125]
	v_mfma_f32_16x16x32_bf16 v[126:129], v[184:187], v[224:227], v[126:129]
	s_nop 7
	s_barrier
	v_and_b32_e32 v241, 63, v131
	v_and_b32_e32 v242, 15, v241
	v_lshrrev_b32_e32 v243, 4, v241
	s_lshr_b32 s56, s50, 1
	s_and_b32 s57, s50, 1
	s_mul_i32 s0, s56, 64*272
	s_lshl_b32 s52, s57, 7
	s_add_i32 s0, s0, s52
	s_add_i32 s0, s0, 16
	v_mul_u32_u24_e32 v244, 1088, v243
	v_lshl_add_u32 v244, v242, 1, v244
	v_add_u32_e32 v229, s0, v244
	s_mul_i32 s0, s57, 64*272
	s_lshl_b32 s52, s56, 7
	s_add_i32 s0, s0, s52
	s_add_i32 s0, s0, 16
	v_mul_u32_u24_e32 v244, 272, v242
	v_lshl_add_u32 v244, v243, 3, v244
	v_add_u32_e32 v230, s0, v244
	s_lshl_b32 s0, s57, 9
	s_lshl_b32 s52, s56, 8
	s_add_i32 s0, s0, s52
	s_add_i32 s0, s0, 16+34816
	v_lshl_add_u32 v228, v243, 4, s0
	s_lshl_b32 s0, s57, 8
	v_lshl_add_u32 v234, v242, 2, s0
	v_lshrrev_b32_e32 v241, 4, v131
	v_and_b32_e32 v242, 15, v131
	v_lshlrev_b32_e32 v242, 4, v242
	v_mul_u32_u24_e32 v243, 272, v241
	v_add3_u32 v231, v243, v242, 16
	s_movk_i32 s0, 0x2500
	v_mad_u32_u24 v232, v241, s0, v242
	v_lshl_add_u32 v233, v241, 12, v242
	s_lshr_b32 s52, s54, 7
	s_mov_b32 s57, 0
	s_movk_i32 s56, 0x170
	s_cmp_lt_u32 s52, 8
	s_cbranch_scc0 .Lin2_t1_v1
	s_mov_b32 s57, 1
	s_movk_i32 s56, 0x28
	s_branch .Lin2_t1_vd
.Lin2_t1_v1:
	s_lshr_b32 s0, s52, 1
	s_cmp_eq_u32 s0, 6
	s_cbranch_scc0 .Lin2_t1_v2
	s_mov_b32 s57, 1
	s_movk_i32 s56, 0x38
	s_branch .Lin2_t1_vd
.Lin2_t1_v2:
	s_cmp_eq_u32 s0, 8
	s_cbranch_scc0 .Lin2_t1_v3
	s_mov_b32 s57, 1
	s_movk_i32 s56, 0x40
	s_branch .Lin2_t1_vd
.Lin2_t1_v3:
	s_cmp_eq_u32 s0, 7
	s_cbranch_scc0 .Lin2_t1_v4
	s_mov_b32 s57, 2
	s_movk_i32 s56, 0x1a8
	s_branch .Lin2_t1_vd
.Lin2_t1_v4:
	s_cmp_eq_u32 s0, 9
	s_cbranch_scc0 .Lin2_t1_vd
	s_mov_b32 s57, 2
	s_movk_i32 s56, 0x1b0
.Lin2_t1_vd:
	s_load_dwordx2 s[40:41], s[12:13], s56
	s_cmp_eq_u32 s57, 1
	s_cbranch_scc0 .Lin2_t1_nonorm
	s_waitcnt lgkmcnt(0)
	global_load_dword v136, v234, s[40:41]
	global_load_dword v137, v234, s[40:41] offset:64
	global_load_dword v138, v234, s[40:41] offset:128
	global_load_dword v139, v234, s[40:41] offset:192
	v_mul_f32_e32 v140, v2, v2
	v_mul_f32_e32 v141, v3, v3
	v_mul_f32_e32 v142, v4, v4
	v_mul_f32_e32 v143, v5, v5
	v_mul_f32_e32 v144, v18, v18
	v_mul_f32_e32 v145, v19, v19
	v_mul_f32_e32 v146, v20, v20
	v_mul_f32_e32 v147, v21, v21
	v_mul_f32_e32 v148, v34, v34
	v_mul_f32_e32 v149, v35, v35
	v_mul_f32_e32 v150, v36, v36
	v_mul_f32_e32 v151, v37, v37
	v_mul_f32_e32 v152, v50, v50
	v_mul_f32_e32 v153, v51, v51
	v_mul_f32_e32 v154, v52, v52
	v_mul_f32_e32 v155, v53, v53
	v_fmac_f32_e32 v140, v6, v6
	v_fmac_f32_e32 v141, v7, v7
	v_fmac_f32_e32 v142, v8, v8
	v_fmac_f32_e32 v143, v9, v9
	v_fmac_f32_e32 v144, v22, v22
	v_fmac_f32_e32 v145, v23, v23
	v_fmac_f32_e32 v146, v24, v24
	v_fmac_f32_e32 v147, v25, v25
	v_fmac_f32_e32 v148, v38, v38
	v_fmac_f32_e32 v149, v39, v39
	v_fmac_f32_e32 v150, v40, v40
	v_fmac_f32_e32 v151, v41, v41
	v_fmac_f32_e32 v152, v54, v54
	v_fmac_f32_e32 v153, v55, v55
	v_fmac_f32_e32 v154, v56, v56
	v_fmac_f32_e32 v155, v57, v57
	v_fmac_f32_e32 v140, v10, v10
	v_fmac_f32_e32 v141, v11, v11
	v_fmac_f32_e32 v142, v12, v12
	v_fmac_f32_e32 v143, v13, v13
	v_fmac_f32_e32 v144, v26, v26
	v_fmac_f32_e32 v145, v27, v27
	v_fmac_f32_e32 v146, v28, v28
	v_fmac_f32_e32 v147, v29, v29
	v_fmac_f32_e32 v148, v42, v42
	v_fmac_f32_e32 v149, v43, v43
	v_fmac_f32_e32 v150, v44, v44
	v_fmac_f32_e32 v151, v45, v45
	v_fmac_f32_e32 v152, v58, v58
	v_fmac_f32_e32 v153, v59, v59
	v_fmac_f32_e32 v154, v60, v60
	v_fmac_f32_e32 v155, v61, v61
	v_fmac_f32_e32 v140, v14, v14
	v_fmac_f32_e32 v141, v15, v15
	v_fmac_f32_e32 v142, v16, v16
	v_fmac_f32_e32 v143, v17, v17
	v_fmac_f32_e32 v144, v30, v30
	v_fmac_f32_e32 v145, v31, v31
	v_fmac_f32_e32 v146, v32, v32
	v_fmac_f32_e32 v147, v33, v33
	v_fmac_f32_e32 v148, v46, v46
	v_fmac_f32_e32 v149, v47, v47
	v_fmac_f32_e32 v150, v48, v48
	v_fmac_f32_e32 v151, v49, v49
	v_fmac_f32_e32 v152, v62, v62
	v_fmac_f32_e32 v153, v63, v63
	v_fmac_f32_e32 v154, v64, v64
	v_fmac_f32_e32 v155, v65, v65
	v_add_f32_dpp v140, v140, v140 quad_perm:[1,0,3,2] row_mask:0xf bank_mask:0xf
	v_add_f32_dpp v141, v141, v141 quad_perm:[1,0,3,2] row_mask:0xf bank_mask:0xf
	v_add_f32_dpp v142, v142, v142 quad_perm:[1,0,3,2] row_mask:0xf bank_mask:0xf
	v_add_f32_dpp v143, v143, v143 quad_perm:[1,0,3,2] row_mask:0xf bank_mask:0xf
	v_add_f32_dpp v144, v144, v144 quad_perm:[1,0,3,2] row_mask:0xf bank_mask:0xf
	v_add_f32_dpp v145, v145, v145 quad_perm:[1,0,3,2] row_mask:0xf bank_mask:0xf
	v_add_f32_dpp v146, v146, v146 quad_perm:[1,0,3,2] row_mask:0xf bank_mask:0xf
	v_add_f32_dpp v147, v147, v147 quad_perm:[1,0,3,2] row_mask:0xf bank_mask:0xf
	v_add_f32_dpp v148, v148, v148 quad_perm:[1,0,3,2] row_mask:0xf bank_mask:0xf
	v_add_f32_dpp v149, v149, v149 quad_perm:[1,0,3,2] row_mask:0xf bank_mask:0xf
	v_add_f32_dpp v150, v150, v150 quad_perm:[1,0,3,2] row_mask:0xf bank_mask:0xf
	v_add_f32_dpp v151, v151, v151 quad_perm:[1,0,3,2] row_mask:0xf bank_mask:0xf
	v_add_f32_dpp v152, v152, v152 quad_perm:[1,0,3,2] row_mask:0xf bank_mask:0xf
	v_add_f32_dpp v153, v153, v153 quad_perm:[1,0,3,2] row_mask:0xf bank_mask:0xf
	v_add_f32_dpp v154, v154, v154 quad_perm:[1,0,3,2] row_mask:0xf bank_mask:0xf
	v_add_f32_dpp v155, v155, v155 quad_perm:[1,0,3,2] row_mask:0xf bank_mask:0xf
	v_add_f32_dpp v140, v140, v140 quad_perm:[2,3,0,1] row_mask:0xf bank_mask:0xf
	v_add_f32_dpp v141, v141, v141 quad_perm:[2,3,0,1] row_mask:0xf bank_mask:0xf
	v_add_f32_dpp v142, v142, v142 quad_perm:[2,3,0,1] row_mask:0xf bank_mask:0xf
	v_add_f32_dpp v143, v143, v143 quad_perm:[2,3,0,1] row_mask:0xf bank_mask:0xf
	v_add_f32_dpp v144, v144, v144 quad_perm:[2,3,0,1] row_mask:0xf bank_mask:0xf
	v_add_f32_dpp v145, v145, v145 quad_perm:[2,3,0,1] row_mask:0xf bank_mask:0xf
	v_add_f32_dpp v146, v146, v146 quad_perm:[2,3,0,1] row_mask:0xf bank_mask:0xf
	v_add_f32_dpp v147, v147, v147 quad_perm:[2,3,0,1] row_mask:0xf bank_mask:0xf
	v_add_f32_dpp v148, v148, v148 quad_perm:[2,3,0,1] row_mask:0xf bank_mask:0xf
	v_add_f32_dpp v149, v149, v149 quad_perm:[2,3,0,1] row_mask:0xf bank_mask:0xf
	v_add_f32_dpp v150, v150, v150 quad_perm:[2,3,0,1] row_mask:0xf bank_mask:0xf
	v_add_f32_dpp v151, v151, v151 quad_perm:[2,3,0,1] row_mask:0xf bank_mask:0xf
	v_add_f32_dpp v152, v152, v152 quad_perm:[2,3,0,1] row_mask:0xf bank_mask:0xf
	v_add_f32_dpp v153, v153, v153 quad_perm:[2,3,0,1] row_mask:0xf bank_mask:0xf
	v_add_f32_dpp v154, v154, v154 quad_perm:[2,3,0,1] row_mask:0xf bank_mask:0xf
	v_add_f32_dpp v155, v155, v155 quad_perm:[2,3,0,1] row_mask:0xf bank_mask:0xf
	v_add_f32_dpp v140, v140, v140 row_half_mirror row_mask:0xf bank_mask:0xf
	v_add_f32_dpp v141, v141, v141 row_half_mirror row_mask:0xf bank_mask:0xf
	v_add_f32_dpp v142, v142, v142 row_half_mirror row_mask:0xf bank_mask:0xf
	v_add_f32_dpp v143, v143, v143 row_half_mirror row_mask:0xf bank_mask:0xf
	v_add_f32_dpp v144, v144, v144 row_half_mirror row_mask:0xf bank_mask:0xf
	v_add_f32_dpp v145, v145, v145 row_half_mirror row_mask:0xf bank_mask:0xf
	v_add_f32_dpp v146, v146, v146 row_half_mirror row_mask:0xf bank_mask:0xf
	v_add_f32_dpp v147, v147, v147 row_half_mirror row_mask:0xf bank_mask:0xf
	v_add_f32_dpp v148, v148, v148 row_half_mirror row_mask:0xf bank_mask:0xf
	v_add_f32_dpp v149, v149, v149 row_half_mirror row_mask:0xf bank_mask:0xf
	v_add_f32_dpp v150, v150, v150 row_half_mirror row_mask:0xf bank_mask:0xf
	v_add_f32_dpp v151, v151, v151 row_half_mirror row_mask:0xf bank_mask:0xf
	v_add_f32_dpp v152, v152, v152 row_half_mirror row_mask:0xf bank_mask:0xf
	v_add_f32_dpp v153, v153, v153 row_half_mirror row_mask:0xf bank_mask:0xf
	v_add_f32_dpp v154, v154, v154 row_half_mirror row_mask:0xf bank_mask:0xf
	v_add_f32_dpp v155, v155, v155 row_half_mirror row_mask:0xf bank_mask:0xf
	v_add_f32_dpp v140, v140, v140 row_mirror row_mask:0xf bank_mask:0xf
	v_add_f32_dpp v141, v141, v141 row_mirror row_mask:0xf bank_mask:0xf
	v_add_f32_dpp v142, v142, v142 row_mirror row_mask:0xf bank_mask:0xf
	v_add_f32_dpp v143, v143, v143 row_mirror row_mask:0xf bank_mask:0xf
	v_add_f32_dpp v144, v144, v144 row_mirror row_mask:0xf bank_mask:0xf
	v_add_f32_dpp v145, v145, v145 row_mirror row_mask:0xf bank_mask:0xf
	v_add_f32_dpp v146, v146, v146 row_mirror row_mask:0xf bank_mask:0xf
	v_add_f32_dpp v147, v147, v147 row_mirror row_mask:0xf bank_mask:0xf
	v_add_f32_dpp v148, v148, v148 row_mirror row_mask:0xf bank_mask:0xf
	v_add_f32_dpp v149, v149, v149 row_mirror row_mask:0xf bank_mask:0xf
	v_add_f32_dpp v150, v150, v150 row_mirror row_mask:0xf bank_mask:0xf
	v_add_f32_dpp v151, v151, v151 row_mirror row_mask:0xf bank_mask:0xf
	v_add_f32_dpp v152, v152, v152 row_mirror row_mask:0xf bank_mask:0xf
	v_add_f32_dpp v153, v153, v153 row_mirror row_mask:0xf bank_mask:0xf
	v_add_f32_dpp v154, v154, v154 row_mirror row_mask:0xf bank_mask:0xf
	v_add_f32_dpp v155, v155, v155 row_mirror row_mask:0xf bank_mask:0xf
	s_mov_b32 exec_lo, 0x10001
	s_mov_b32 exec_hi, 0x10001
	ds_write_b128 v228, v[140:143]
	ds_write_b128 v228, v[144:147] offset:64
	ds_write_b128 v228, v[148:151] offset:128
	ds_write_b128 v228, v[152:155] offset:192
	s_mov_b64 exec, -1
	s_waitcnt lgkmcnt(0)
	s_barrier
	v_and_b32_e32 v241, 0xfffffdff, v228
	ds_read_b128 v[172:175], v241
	ds_read_b128 v[176:179], v241 offset:64
	ds_read_b128 v[180:183], v241 offset:128
	ds_read_b128 v[184:187], v241 offset:192
	ds_read_b128 v[196:199], v241 offset:512
	ds_read_b128 v[200:203], v241 offset:576
	ds_read_b128 v[204:207], v241 offset:640
	ds_read_b128 v[212:215], v241 offset:704
	v_mov_b32_e32 v242, 0x3c000000
	v_mov_b32_e32 v243, 0x358637bd
	s_waitcnt lgkmcnt(3)
	s_waitcnt lgkmcnt(2)
	s_waitcnt lgkmcnt(1)
	s_waitcnt lgkmcnt(0)
	s_waitcnt lgkmcnt(0)
	v_add_f32_e32 v172, v172, v196
	v_add_f32_e32 v173, v173, v197
	v_add_f32_e32 v174, v174, v198
	v_add_f32_e32 v175, v175, v199
	v_add_f32_e32 v176, v176, v200
	v_add_f32_e32 v177, v177, v201
	v_add_f32_e32 v178, v178, v202
	v_add_f32_e32 v179, v179, v203
	v_add_f32_e32 v180, v180, v204
	v_add_f32_e32 v181, v181, v205
	v_add_f32_e32 v182, v182, v206
	v_add_f32_e32 v183, v183, v207
	v_add_f32_e32 v184, v184, v212
	v_add_f32_e32 v185, v185, v213
	v_add_f32_e32 v186, v186, v214
	v_add_f32_e32 v187, v187, v215
	v_fma_f32 v172, v172, v242, v243
	v_fma_f32 v173, v173, v242, v243
	v_fma_f32 v174, v174, v242, v243
	v_fma_f32 v175, v175, v242, v243
	v_fma_f32 v176, v176, v242, v243
	v_fma_f32 v177, v177, v242, v243
	v_fma_f32 v178, v178, v242, v243
	v_fma_f32 v179, v179, v242, v243
	v_fma_f32 v180, v180, v242, v243
	v_fma_f32 v181, v181, v242, v243
	v_fma_f32 v182, v182, v242, v243
	v_fma_f32 v183, v183, v242, v243
	v_fma_f32 v184, v184, v242, v243
	v_fma_f32 v185, v185, v242, v243
	v_fma_f32 v186, v186, v242, v243
	v_fma_f32 v187, v187, v242, v243
	v_rsq_f32_e32 v172, v172
	v_rsq_f32_e32 v173, v173
	v_rsq_f32_e32 v174, v174
	v_rsq_f32_e32 v175, v175
	v_rsq_f32_e32 v176, v176
	v_rsq_f32_e32 v177, v177
	v_rsq_f32_e32 v178, v178
	v_rsq_f32_e32 v179, v179
	v_rsq_f32_e32 v180, v180
	v_rsq_f32_e32 v181, v181
	v_rsq_f32_e32 v182, v182
	v_rsq_f32_e32 v183, v183
	v_rsq_f32_e32 v184, v184
	v_rsq_f32_e32 v185, v185
	v_rsq_f32_e32 v186, v186
	v_rsq_f32_e32 v187, v187
	s_waitcnt vmcnt(0)
	v_mul_f32_e32 v2, v2, v172
	v_mul_f32_e32 v3, v3, v173
	v_mul_f32_e32 v4, v4, v174
	v_mul_f32_e32 v5, v5, v175
	v_mul_f32_e32 v6, v6, v172
	v_mul_f32_e32 v7, v7, v173
	v_mul_f32_e32 v8, v8, v174
	v_mul_f32_e32 v9, v9, v175
	v_mul_f32_e32 v10, v10, v172
	v_mul_f32_e32 v11, v11, v173
	v_mul_f32_e32 v12, v12, v174
	v_mul_f32_e32 v13, v13, v175
	v_mul_f32_e32 v14, v14, v172
	v_mul_f32_e32 v15, v15, v173
	v_mul_f32_e32 v16, v16, v174
	v_mul_f32_e32 v17, v17, v175
	v_mul_f32_e32 v18, v18, v176
	v_mul_f32_e32 v19, v19, v177
	v_mul_f32_e32 v20, v20, v178
	v_mul_f32_e32 v21, v21, v179
	v_mul_f32_e32 v22, v22, v176
	v_mul_f32_e32 v23, v23, v177
	v_mul_f32_e32 v24, v24, v178
	v_mul_f32_e32 v25, v25, v179
	v_mul_f32_e32 v26, v26, v176
	v_mul_f32_e32 v27, v27, v177
	v_mul_f32_e32 v28, v28, v178
	v_mul_f32_e32 v29, v29, v179
	v_mul_f32_e32 v30, v30, v176
	v_mul_f32_e32 v31, v31, v177
	v_mul_f32_e32 v32, v32, v178
	v_mul_f32_e32 v33, v33, v179
	v_mul_f32_e32 v34, v34, v180
	v_mul_f32_e32 v35, v35, v181
	v_mul_f32_e32 v36, v36, v182
	v_mul_f32_e32 v37, v37, v183
	v_mul_f32_e32 v38, v38, v180
	v_mul_f32_e32 v39, v39, v181
	v_mul_f32_e32 v40, v40, v182
	v_mul_f32_e32 v41, v41, v183
	v_mul_f32_e32 v42, v42, v180
	v_mul_f32_e32 v43, v43, v181
	v_mul_f32_e32 v44, v44, v182
	v_mul_f32_e32 v45, v45, v183
	v_mul_f32_e32 v46, v46, v180
	v_mul_f32_e32 v47, v47, v181
	v_mul_f32_e32 v48, v48, v182
	v_mul_f32_e32 v49, v49, v183
	v_mul_f32_e32 v50, v50, v184
	v_mul_f32_e32 v51, v51, v185
	v_mul_f32_e32 v52, v52, v186
	v_mul_f32_e32 v53, v53, v187
	v_mul_f32_e32 v54, v54, v184
	v_mul_f32_e32 v55, v55, v185
	v_mul_f32_e32 v56, v56, v186
	v_mul_f32_e32 v57, v57, v187
	v_mul_f32_e32 v58, v58, v184
	v_mul_f32_e32 v59, v59, v185
	v_mul_f32_e32 v60, v60, v186
	v_mul_f32_e32 v61, v61, v187
	v_mul_f32_e32 v62, v62, v184
	v_mul_f32_e32 v63, v63, v185
	v_mul_f32_e32 v64, v64, v186
	v_mul_f32_e32 v65, v65, v187
	v_mul_f32_e32 v2, v2, v136
	v_mul_f32_e32 v3, v3, v136
	v_mul_f32_e32 v4, v4, v136
	v_mul_f32_e32 v5, v5, v136
	v_mul_f32_e32 v6, v6, v137
	v_mul_f32_e32 v7, v7, v137
	v_mul_f32_e32 v8, v8, v137
	v_mul_f32_e32 v9, v9, v137
	v_mul_f32_e32 v10, v10, v138
	v_mul_f32_e32 v11, v11, v138
	v_mul_f32_e32 v12, v12, v138
	v_mul_f32_e32 v13, v13, v138
	v_mul_f32_e32 v14, v14, v139
	v_mul_f32_e32 v15, v15, v139
	v_mul_f32_e32 v16, v16, v139
	v_mul_f32_e32 v17, v17, v139
	v_mul_f32_e32 v18, v18, v136
	v_mul_f32_e32 v19, v19, v136
	v_mul_f32_e32 v20, v20, v136
	v_mul_f32_e32 v21, v21, v136
	v_mul_f32_e32 v22, v22, v137
	v_mul_f32_e32 v23, v23, v137
	v_mul_f32_e32 v24, v24, v137
	v_mul_f32_e32 v25, v25, v137
	v_mul_f32_e32 v26, v26, v138
	v_mul_f32_e32 v27, v27, v138
	v_mul_f32_e32 v28, v28, v138
	v_mul_f32_e32 v29, v29, v138
	v_mul_f32_e32 v30, v30, v139
	v_mul_f32_e32 v31, v31, v139
	v_mul_f32_e32 v32, v32, v139
	v_mul_f32_e32 v33, v33, v139
	v_mul_f32_e32 v34, v34, v136
	v_mul_f32_e32 v35, v35, v136
	v_mul_f32_e32 v36, v36, v136
	v_mul_f32_e32 v37, v37, v136
	v_mul_f32_e32 v38, v38, v137
	v_mul_f32_e32 v39, v39, v137
	v_mul_f32_e32 v40, v40, v137
	v_mul_f32_e32 v41, v41, v137
	v_mul_f32_e32 v42, v42, v138
	v_mul_f32_e32 v43, v43, v138
	v_mul_f32_e32 v44, v44, v138
	v_mul_f32_e32 v45, v45, v138
	v_mul_f32_e32 v46, v46, v139
	v_mul_f32_e32 v47, v47, v139
	v_mul_f32_e32 v48, v48, v139
	v_mul_f32_e32 v49, v49, v139
	v_mul_f32_e32 v50, v50, v136
	v_mul_f32_e32 v51, v51, v136
	v_mul_f32_e32 v52, v52, v136
	v_mul_f32_e32 v53, v53, v136
	v_mul_f32_e32 v54, v54, v137
	v_mul_f32_e32 v55, v55, v137
	v_mul_f32_e32 v56, v56, v137
	v_mul_f32_e32 v57, v57, v137
	v_mul_f32_e32 v58, v58, v138
	v_mul_f32_e32 v59, v59, v138
	v_mul_f32_e32 v60, v60, v138
	v_mul_f32_e32 v61, v61, v138
	v_mul_f32_e32 v62, v62, v139
	v_mul_f32_e32 v63, v63, v139
	v_mul_f32_e32 v64, v64, v139
	v_mul_f32_e32 v65, v65, v139
	s_movk_i32 s56, 0x170
	s_load_dwordx2 s[40:41], s[12:13], s56
.Lin2_t1_nonorm:
	s_cmp_eq_u32 s57, 2
	s_cbranch_scc1 .Lin2_t1_trans
	v_cvt_pk_bf16_f32 v2, v2, v6
	ds_write_b16 v229, v2
	ds_write_b16_d16_hi v229, v2 offset:32
	v_cvt_pk_bf16_f32 v10, v10, v14
	ds_write_b16 v229, v10 offset:64
	ds_write_b16_d16_hi v229, v10 offset:96
	v_cvt_pk_bf16_f32 v3, v3, v7
	ds_write_b16 v229, v3 offset:272
	ds_write_b16_d16_hi v229, v3 offset:304
	v_cvt_pk_bf16_f32 v11, v11, v15
	ds_write_b16 v229, v11 offset:336
	ds_write_b16_d16_hi v229, v11 offset:368
	v_cvt_pk_bf16_f32 v4, v4, v8
	ds_write_b16 v229, v4 offset:544
	ds_write_b16_d16_hi v229, v4 offset:576
	v_cvt_pk_bf16_f32 v12, v12, v16
	ds_write_b16 v229, v12 offset:608
	ds_write_b16_d16_hi v229, v12 offset:640
	v_cvt_pk_bf16_f32 v5, v5, v9
	ds_write_b16 v229, v5 offset:816
	ds_write_b16_d16_hi v229, v5 offset:848
	v_cvt_pk_bf16_f32 v13, v13, v17
	ds_write_b16 v229, v13 offset:880
	ds_write_b16_d16_hi v229, v13 offset:912
	v_cvt_pk_bf16_f32 v18, v18, v22
	ds_write_b16 v229, v18 offset:4352
	ds_write_b16_d16_hi v229, v18 offset:4384
	v_cvt_pk_bf16_f32 v26, v26, v30
	ds_write_b16 v229, v26 offset:4416
	ds_write_b16_d16_hi v229, v26 offset:4448
	v_cvt_pk_bf16_f32 v19, v19, v23
	ds_write_b16 v229, v19 offset:4624
	ds_write_b16_d16_hi v229, v19 offset:4656
	v_cvt_pk_bf16_f32 v27, v27, v31
	ds_write_b16 v229, v27 offset:4688
	ds_write_b16_d16_hi v229, v27 offset:4720
	v_cvt_pk_bf16_f32 v20, v20, v24
	ds_write_b16 v229, v20 offset:4896
	ds_write_b16_d16_hi v229, v20 offset:4928
	v_cvt_pk_bf16_f32 v28, v28, v32
	ds_write_b16 v229, v28 offset:4960
	ds_write_b16_d16_hi v229, v28 offset:4992
	v_cvt_pk_bf16_f32 v21, v21, v25
	ds_write_b16 v229, v21 offset:5168
	ds_write_b16_d16_hi v229, v21 offset:5200
	v_cvt_pk_bf16_f32 v29, v29, v33
	ds_write_b16 v229, v29 offset:5232
	ds_write_b16_d16_hi v229, v29 offset:5264
	v_cvt_pk_bf16_f32 v34, v34, v38
	ds_write_b16 v229, v34 offset:8704
	ds_write_b16_d16_hi v229, v34 offset:8736
	v_cvt_pk_bf16_f32 v42, v42, v46
	ds_write_b16 v229, v42 offset:8768
	ds_write_b16_d16_hi v229, v42 offset:8800
	v_cvt_pk_bf16_f32 v35, v35, v39
	ds_write_b16 v229, v35 offset:8976
	ds_write_b16_d16_hi v229, v35 offset:9008
	v_cvt_pk_bf16_f32 v43, v43, v47
	ds_write_b16 v229, v43 offset:9040
	ds_write_b16_d16_hi v229, v43 offset:9072
	v_cvt_pk_bf16_f32 v36, v36, v40
	ds_write_b16 v229, v36 offset:9248
	ds_write_b16_d16_hi v229, v36 offset:9280
	v_cvt_pk_bf16_f32 v44, v44, v48
	ds_write_b16 v229, v44 offset:9312
	ds_write_b16_d16_hi v229, v44 offset:9344
	v_cvt_pk_bf16_f32 v37, v37, v41
	ds_write_b16 v229, v37 offset:9520
	ds_write_b16_d16_hi v229, v37 offset:9552
	v_cvt_pk_bf16_f32 v45, v45, v49
	ds_write_b16 v229, v45 offset:9584
	ds_write_b16_d16_hi v229, v45 offset:9616
	v_cvt_pk_bf16_f32 v50, v50, v54
	ds_write_b16 v229, v50 offset:13056
	ds_write_b16_d16_hi v229, v50 offset:13088
	v_cvt_pk_bf16_f32 v58, v58, v62
	ds_write_b16 v229, v58 offset:13120
	ds_write_b16_d16_hi v229, v58 offset:13152
	v_cvt_pk_bf16_f32 v51, v51, v55
	ds_write_b16 v229, v51 offset:13328
	ds_write_b16_d16_hi v229, v51 offset:13360
	v_cvt_pk_bf16_f32 v59, v59, v63
	ds_write_b16 v229, v59 offset:13392
	ds_write_b16_d16_hi v229, v59 offset:13424
	v_cvt_pk_bf16_f32 v52, v52, v56
	ds_write_b16 v229, v52 offset:13600
	ds_write_b16_d16_hi v229, v52 offset:13632
	v_cvt_pk_bf16_f32 v60, v60, v64
	ds_write_b16 v229, v60 offset:13664
	ds_write_b16_d16_hi v229, v60 offset:13696
	v_cvt_pk_bf16_f32 v53, v53, v57
	ds_write_b16 v229, v53 offset:13872
	ds_write_b16_d16_hi v229, v53 offset:13904
	v_cvt_pk_bf16_f32 v61, v61, v65
	ds_write_b16 v229, v61 offset:13936
	ds_write_b16_d16_hi v229, v61 offset:13968
	s_mul_i32 s0, s53, 0x2500
	s_lshl_b32 s56, s52, 8
	s_add_i32 s0, s0, s56
	s_waitcnt lgkmcnt(0)
	s_add_u32 s58, s40, s0
	s_addc_u32 s59, s41, 0
	s_mov_b32 s56, 0x25000
	v_mov_b32_e32 v241, v232
	s_branch .Lin2_t1_store
.Lin2_t1_trans:
	v_cvt_pk_bf16_f32 v2, v2, v3
	v_cvt_pk_bf16_f32 v3, v4, v5
	ds_write_b64 v230, v[2:3]
	v_cvt_pk_bf16_f32 v6, v6, v7
	v_cvt_pk_bf16_f32 v7, v8, v9
	ds_write_b64 v230, v[6:7] offset:4352
	v_cvt_pk_bf16_f32 v10, v10, v11
	v_cvt_pk_bf16_f32 v11, v12, v13
	ds_write_b64 v230, v[10:11] offset:8704
	v_cvt_pk_bf16_f32 v14, v14, v15
	v_cvt_pk_bf16_f32 v15, v16, v17
	ds_write_b64 v230, v[14:15] offset:13056
	v_cvt_pk_bf16_f32 v18, v18, v19
	v_cvt_pk_bf16_f32 v19, v20, v21
	ds_write_b64 v230, v[18:19] offset:32
	v_cvt_pk_bf16_f32 v22, v22, v23
	v_cvt_pk_bf16_f32 v23, v24, v25
	ds_write_b64 v230, v[22:23] offset:4384
	v_cvt_pk_bf16_f32 v26, v26, v27
	v_cvt_pk_bf16_f32 v27, v28, v29
	ds_write_b64 v230, v[26:27] offset:8736
	v_cvt_pk_bf16_f32 v30, v30, v31
	v_cvt_pk_bf16_f32 v31, v32, v33
	ds_write_b64 v230, v[30:31] offset:13088
	v_cvt_pk_bf16_f32 v34, v34, v35
	v_cvt_pk_bf16_f32 v35, v36, v37
	ds_write_b64 v230, v[34:35] offset:64
	v_cvt_pk_bf16_f32 v38, v38, v39
	v_cvt_pk_bf16_f32 v39, v40, v41
	ds_write_b64 v230, v[38:39] offset:4416
	v_cvt_pk_bf16_f32 v42, v42, v43
	v_cvt_pk_bf16_f32 v43, v44, v45
	ds_write_b64 v230, v[42:43] offset:8768
	v_cvt_pk_bf16_f32 v46, v46, v47
	v_cvt_pk_bf16_f32 v47, v48, v49
	ds_write_b64 v230, v[46:47] offset:13120
	v_cvt_pk_bf16_f32 v50, v50, v51
	v_cvt_pk_bf16_f32 v51, v52, v53
	ds_write_b64 v230, v[50:51] offset:96
	v_cvt_pk_bf16_f32 v54, v54, v55
	v_cvt_pk_bf16_f32 v55, v56, v57
	ds_write_b64 v230, v[54:55] offset:4448
	v_cvt_pk_bf16_f32 v58, v58, v59
	v_cvt_pk_bf16_f32 v59, v60, v61
	ds_write_b64 v230, v[58:59] offset:8800
	v_cvt_pk_bf16_f32 v62, v62, v63
	v_cvt_pk_bf16_f32 v63, v64, v65
	ds_write_b64 v230, v[62:63] offset:13152
	s_lshr_b32 s0, s53, 11
	s_lshl_b32 s0, s0, 1
	s_and_b32 s56, s52, 1
	s_add_i32 s0, s0, s56
	s_lshl_b32 s0, s0, 19
	s_lshr_b32 s56, s53, 7
	s_and_b32 s56, s56, 15
	s_lshl_b32 s56, s56, 8
	s_add_i32 s0, s0, s56
	s_waitcnt lgkmcnt(0)
	s_add_u32 s58, s40, s0
	s_addc_u32 s59, s41, 0
	s_mov_b32 s56, 0x10000
	v_mov_b32_e32 v241, v233
.Lin2_t1_store:
	s_waitcnt lgkmcnt(0)
	s_barrier
	ds_read_b128 v[172:175], v231
	ds_read_b128 v[176:179], v231 offset:4352
	ds_read_b128 v[180:183], v231 offset:8704
	ds_read_b128 v[184:187], v231 offset:13056
	ds_read_b128 v[196:199], v231 offset:17408
	ds_read_b128 v[200:203], v231 offset:21760
	ds_read_b128 v[204:207], v231 offset:26112
	ds_read_b128 v[212:215], v231 offset:30464
	s_waitcnt lgkmcnt(7)
	global_store_dwordx4 v241, v[172:175], s[58:59]
	s_add_u32 s58, s58, s56
	s_addc_u32 s59, s59, 0
	s_waitcnt lgkmcnt(6)
	global_store_dwordx4 v241, v[176:179], s[58:59]
	s_add_u32 s58, s58, s56
	s_addc_u32 s59, s59, 0
	s_waitcnt lgkmcnt(5)
	global_store_dwordx4 v241, v[180:183], s[58:59]
	s_add_u32 s58, s58, s56
	s_addc_u32 s59, s59, 0
	s_waitcnt lgkmcnt(4)
	global_store_dwordx4 v241, v[184:187], s[58:59]
	s_add_u32 s58, s58, s56
	s_addc_u32 s59, s59, 0
	s_waitcnt lgkmcnt(3)
	global_store_dwordx4 v241, v[196:199], s[58:59]
	s_add_u32 s58, s58, s56
	s_addc_u32 s59, s59, 0
	s_waitcnt lgkmcnt(2)
	global_store_dwordx4 v241, v[200:203], s[58:59]
	s_add_u32 s58, s58, s56
	s_addc_u32 s59, s59, 0
	s_waitcnt lgkmcnt(1)
	global_store_dwordx4 v241, v[204:207], s[58:59]
	s_add_u32 s58, s58, s56
	s_addc_u32 s59, s59, 0
	s_waitcnt lgkmcnt(0)
	global_store_dwordx4 v241, v[212:215], s[58:59]
	s_barrier
	s_lshr_b32 s52, s54, 7
	s_add_i32 s52, s52, 8
	s_mov_b32 s57, 0
	s_movk_i32 s56, 0x170
	s_cmp_lt_u32 s52, 8
	s_cbranch_scc0 .Lin2_t2_v1
	s_mov_b32 s57, 1
	s_movk_i32 s56, 0x28
	s_branch .Lin2_t2_vd

.Lin2_t2_vd:
	s_load_dwordx2 s[40:41], s[12:13], s56
	s_cmp_eq_u32 s57, 1
	s_cbranch_scc0 .Lin2_t2_nonorm
	s_waitcnt lgkmcnt(0)
	global_load_dword v136, v234, s[40:41]
	global_load_dword v137, v234, s[40:41] offset:64
	global_load_dword v138, v234, s[40:41] offset:128
	global_load_dword v139, v234, s[40:41] offset:192
	v_mul_f32_e32 v140, v66, v66
	v_mul_f32_e32 v141, v67, v67
	v_mul_f32_e32 v142, v68, v68
	v_mul_f32_e32 v143, v69, v69
	v_mul_f32_e32 v144, v82, v82
	v_mul_f32_e32 v145, v83, v83
	v_mul_f32_e32 v146, v84, v84
	v_mul_f32_e32 v147, v85, v85
	v_mul_f32_e32 v148, v98, v98
	v_mul_f32_e32 v149, v99, v99
	v_mul_f32_e32 v150, v100, v100
	v_mul_f32_e32 v151, v101, v101
	v_mul_f32_e32 v152, v114, v114
	v_mul_f32_e32 v153, v115, v115
	v_mul_f32_e32 v154, v116, v116
	v_mul_f32_e32 v155, v117, v117
	v_fmac_f32_e32 v140, v70, v70
	v_fmac_f32_e32 v141, v71, v71
	v_fmac_f32_e32 v142, v72, v72
	v_fmac_f32_e32 v143, v73, v73
	v_fmac_f32_e32 v144, v86, v86
	v_fmac_f32_e32 v145, v87, v87
	v_fmac_f32_e32 v146, v88, v88
	v_fmac_f32_e32 v147, v89, v89
	v_fmac_f32_e32 v148, v102, v102
	v_fmac_f32_e32 v149, v103, v103
	v_fmac_f32_e32 v150, v104, v104
	v_fmac_f32_e32 v151, v105, v105
	v_fmac_f32_e32 v152, v118, v118
	v_fmac_f32_e32 v153, v119, v119
	v_fmac_f32_e32 v154, v120, v120
	v_fmac_f32_e32 v155, v121, v121
	v_fmac_f32_e32 v140, v74, v74
	v_fmac_f32_e32 v141, v75, v75
	v_fmac_f32_e32 v142, v76, v76
	v_fmac_f32_e32 v143, v77, v77
	v_fmac_f32_e32 v144, v90, v90
	v_fmac_f32_e32 v145, v91, v91
	v_fmac_f32_e32 v146, v92, v92
	v_fmac_f32_e32 v147, v93, v93
	v_fmac_f32_e32 v148, v106, v106
	v_fmac_f32_e32 v149, v107, v107
	v_fmac_f32_e32 v150, v108, v108
	v_fmac_f32_e32 v151, v109, v109
	v_fmac_f32_e32 v152, v122, v122
	v_fmac_f32_e32 v153, v123, v123
	v_fmac_f32_e32 v154, v124, v124
	v_fmac_f32_e32 v155, v125, v125
	v_fmac_f32_e32 v140, v78, v78
	v_fmac_f32_e32 v141, v79, v79
	v_fmac_f32_e32 v142, v80, v80
	v_fmac_f32_e32 v143, v81, v81
	v_fmac_f32_e32 v144, v94, v94
	v_fmac_f32_e32 v145, v95, v95
	v_fmac_f32_e32 v146, v96, v96
	v_fmac_f32_e32 v147, v97, v97
	v_fmac_f32_e32 v148, v110, v110
	v_fmac_f32_e32 v149, v111, v111
	v_fmac_f32_e32 v150, v112, v112
	v_fmac_f32_e32 v151, v113, v113
	v_fmac_f32_e32 v152, v126, v126
	v_fmac_f32_e32 v153, v127, v127
	v_fmac_f32_e32 v154, v128, v128
	v_fmac_f32_e32 v155, v129, v129
	v_add_f32_dpp v140, v140, v140 quad_perm:[1,0,3,2] row_mask:0xf bank_mask:0xf
	v_add_f32_dpp v141, v141, v141 quad_perm:[1,0,3,2] row_mask:0xf bank_mask:0xf
	v_add_f32_dpp v142, v142, v142 quad_perm:[1,0,3,2] row_mask:0xf bank_mask:0xf
	v_add_f32_dpp v143, v143, v143 quad_perm:[1,0,3,2] row_mask:0xf bank_mask:0xf
	v_add_f32_dpp v144, v144, v144 quad_perm:[1,0,3,2] row_mask:0xf bank_mask:0xf
	v_add_f32_dpp v145, v145, v145 quad_perm:[1,0,3,2] row_mask:0xf bank_mask:0xf
	v_add_f32_dpp v146, v146, v146 quad_perm:[1,0,3,2] row_mask:0xf bank_mask:0xf
	v_add_f32_dpp v147, v147, v147 quad_perm:[1,0,3,2] row_mask:0xf bank_mask:0xf
	v_add_f32_dpp v148, v148, v148 quad_perm:[1,0,3,2] row_mask:0xf bank_mask:0xf
	v_add_f32_dpp v149, v149, v149 quad_perm:[1,0,3,2] row_mask:0xf bank_mask:0xf
	v_add_f32_dpp v150, v150, v150 quad_perm:[1,0,3,2] row_mask:0xf bank_mask:0xf
	v_add_f32_dpp v151, v151, v151 quad_perm:[1,0,3,2] row_mask:0xf bank_mask:0xf
	v_add_f32_dpp v152, v152, v152 quad_perm:[1,0,3,2] row_mask:0xf bank_mask:0xf
	v_add_f32_dpp v153, v153, v153 quad_perm:[1,0,3,2] row_mask:0xf bank_mask:0xf
	v_add_f32_dpp v154, v154, v154 quad_perm:[1,0,3,2] row_mask:0xf bank_mask:0xf
	v_add_f32_dpp v155, v155, v155 quad_perm:[1,0,3,2] row_mask:0xf bank_mask:0xf
	v_add_f32_dpp v140, v140, v140 quad_perm:[2,3,0,1] row_mask:0xf bank_mask:0xf
	v_add_f32_dpp v141, v141, v141 quad_perm:[2,3,0,1] row_mask:0xf bank_mask:0xf
	v_add_f32_dpp v142, v142, v142 quad_perm:[2,3,0,1] row_mask:0xf bank_mask:0xf
	v_add_f32_dpp v143, v143, v143 quad_perm:[2,3,0,1] row_mask:0xf bank_mask:0xf
	v_add_f32_dpp v144, v144, v144 quad_perm:[2,3,0,1] row_mask:0xf bank_mask:0xf
	v_add_f32_dpp v145, v145, v145 quad_perm:[2,3,0,1] row_mask:0xf bank_mask:0xf
	v_add_f32_dpp v146, v146, v146 quad_perm:[2,3,0,1] row_mask:0xf bank_mask:0xf
	v_add_f32_dpp v147, v147, v147 quad_perm:[2,3,0,1] row_mask:0xf bank_mask:0xf
	v_add_f32_dpp v148, v148, v148 quad_perm:[2,3,0,1] row_mask:0xf bank_mask:0xf
	v_add_f32_dpp v149, v149, v149 quad_perm:[2,3,0,1] row_mask:0xf bank_mask:0xf
	v_add_f32_dpp v150, v150, v150 quad_perm:[2,3,0,1] row_mask:0xf bank_mask:0xf
	v_add_f32_dpp v151, v151, v151 quad_perm:[2,3,0,1] row_mask:0xf bank_mask:0xf
	v_add_f32_dpp v152, v152, v152 quad_perm:[2,3,0,1] row_mask:0xf bank_mask:0xf
	v_add_f32_dpp v153, v153, v153 quad_perm:[2,3,0,1] row_mask:0xf bank_mask:0xf
	v_add_f32_dpp v154, v154, v154 quad_perm:[2,3,0,1] row_mask:0xf bank_mask:0xf
	v_add_f32_dpp v155, v155, v155 quad_perm:[2,3,0,1] row_mask:0xf bank_mask:0xf
	v_add_f32_dpp v140, v140, v140 row_half_mirror row_mask:0xf bank_mask:0xf
	v_add_f32_dpp v141, v141, v141 row_half_mirror row_mask:0xf bank_mask:0xf
	v_add_f32_dpp v142, v142, v142 row_half_mirror row_mask:0xf bank_mask:0xf
	v_add_f32_dpp v143, v143, v143 row_half_mirror row_mask:0xf bank_mask:0xf
	v_add_f32_dpp v144, v144, v144 row_half_mirror row_mask:0xf bank_mask:0xf
	v_add_f32_dpp v145, v145, v145 row_half_mirror row_mask:0xf bank_mask:0xf
	v_add_f32_dpp v146, v146, v146 row_half_mirror row_mask:0xf bank_mask:0xf
	v_add_f32_dpp v147, v147, v147 row_half_mirror row_mask:0xf bank_mask:0xf
	v_add_f32_dpp v148, v148, v148 row_half_mirror row_mask:0xf bank_mask:0xf
	v_add_f32_dpp v149, v149, v149 row_half_mirror row_mask:0xf bank_mask:0xf
	v_add_f32_dpp v150, v150, v150 row_half_mirror row_mask:0xf bank_mask:0xf
	v_add_f32_dpp v151, v151, v151 row_half_mirror row_mask:0xf bank_mask:0xf
	v_add_f32_dpp v152, v152, v152 row_half_mirror row_mask:0xf bank_mask:0xf
	v_add_f32_dpp v153, v153, v153 row_half_mirror row_mask:0xf bank_mask:0xf
	v_add_f32_dpp v154, v154, v154 row_half_mirror row_mask:0xf bank_mask:0xf
	v_add_f32_dpp v155, v155, v155 row_half_mirror row_mask:0xf bank_mask:0xf
	v_add_f32_dpp v140, v140, v140 row_mirror row_mask:0xf bank_mask:0xf
	v_add_f32_dpp v141, v141, v141 row_mirror row_mask:0xf bank_mask:0xf
	v_add_f32_dpp v142, v142, v142 row_mirror row_mask:0xf bank_mask:0xf
	v_add_f32_dpp v143, v143, v143 row_mirror row_mask:0xf bank_mask:0xf
	v_add_f32_dpp v144, v144, v144 row_mirror row_mask:0xf bank_mask:0xf
	v_add_f32_dpp v145, v145, v145 row_mirror row_mask:0xf bank_mask:0xf
	v_add_f32_dpp v146, v146, v146 row_mirror row_mask:0xf bank_mask:0xf
	v_add_f32_dpp v147, v147, v147 row_mirror row_mask:0xf bank_mask:0xf
	v_add_f32_dpp v148, v148, v148 row_mirror row_mask:0xf bank_mask:0xf
	v_add_f32_dpp v149, v149, v149 row_mirror row_mask:0xf bank_mask:0xf
	v_add_f32_dpp v150, v150, v150 row_mirror row_mask:0xf bank_mask:0xf
	v_add_f32_dpp v151, v151, v151 row_mirror row_mask:0xf bank_mask:0xf
	v_add_f32_dpp v152, v152, v152 row_mirror row_mask:0xf bank_mask:0xf
	v_add_f32_dpp v153, v153, v153 row_mirror row_mask:0xf bank_mask:0xf
	v_add_f32_dpp v154, v154, v154 row_mirror row_mask:0xf bank_mask:0xf
	v_add_f32_dpp v155, v155, v155 row_mirror row_mask:0xf bank_mask:0xf
	s_mov_b32 exec_lo, 0x10001
	s_mov_b32 exec_hi, 0x10001
	ds_write_b128 v228, v[140:143]
	ds_write_b128 v228, v[144:147] offset:64
	ds_write_b128 v228, v[148:151] offset:128
	ds_write_b128 v228, v[152:155] offset:192
	s_mov_b64 exec, -1
	s_waitcnt lgkmcnt(0)
	s_barrier
	v_and_b32_e32 v241, 0xfffffdff, v228
	ds_read_b128 v[172:175], v241
	ds_read_b128 v[176:179], v241 offset:64
	ds_read_b128 v[180:183], v241 offset:128
	ds_read_b128 v[184:187], v241 offset:192
	ds_read_b128 v[196:199], v241 offset:512
	ds_read_b128 v[200:203], v241 offset:576
	ds_read_b128 v[204:207], v241 offset:640
	ds_read_b128 v[212:215], v241 offset:704
	v_mov_b32_e32 v242, 0x3c000000
	v_mov_b32_e32 v243, 0x358637bd
	s_waitcnt lgkmcnt(3)
	s_waitcnt lgkmcnt(2)
	s_waitcnt lgkmcnt(1)
	s_waitcnt lgkmcnt(0)
	s_waitcnt lgkmcnt(0)
	v_add_f32_e32 v172, v172, v196
	v_add_f32_e32 v173, v173, v197
	v_add_f32_e32 v174, v174, v198
	v_add_f32_e32 v175, v175, v199
	v_add_f32_e32 v176, v176, v200
	v_add_f32_e32 v177, v177, v201
	v_add_f32_e32 v178, v178, v202
	v_add_f32_e32 v179, v179, v203
	v_add_f32_e32 v180, v180, v204
	v_add_f32_e32 v181, v181, v205
	v_add_f32_e32 v182, v182, v206
	v_add_f32_e32 v183, v183, v207
	v_add_f32_e32 v184, v184, v212
	v_add_f32_e32 v185, v185, v213
	v_add_f32_e32 v186, v186, v214
	v_add_f32_e32 v187, v187, v215
	v_fma_f32 v172, v172, v242, v243
	v_fma_f32 v173, v173, v242, v243
	v_fma_f32 v174, v174, v242, v243
	v_fma_f32 v175, v175, v242, v243
	v_fma_f32 v176, v176, v242, v243
	v_fma_f32 v177, v177, v242, v243
	v_fma_f32 v178, v178, v242, v243
	v_fma_f32 v179, v179, v242, v243
	v_fma_f32 v180, v180, v242, v243
	v_fma_f32 v181, v181, v242, v243
	v_fma_f32 v182, v182, v242, v243
	v_fma_f32 v183, v183, v242, v243
	v_fma_f32 v184, v184, v242, v243
	v_fma_f32 v185, v185, v242, v243
	v_fma_f32 v186, v186, v242, v243
	v_fma_f32 v187, v187, v242, v243
	v_rsq_f32_e32 v172, v172
	v_rsq_f32_e32 v173, v173
	v_rsq_f32_e32 v174, v174
	v_rsq_f32_e32 v175, v175
	v_rsq_f32_e32 v176, v176
	v_rsq_f32_e32 v177, v177
	v_rsq_f32_e32 v178, v178
	v_rsq_f32_e32 v179, v179
	v_rsq_f32_e32 v180, v180
	v_rsq_f32_e32 v181, v181
	v_rsq_f32_e32 v182, v182
	v_rsq_f32_e32 v183, v183
	v_rsq_f32_e32 v184, v184
	v_rsq_f32_e32 v185, v185
	v_rsq_f32_e32 v186, v186
	v_rsq_f32_e32 v187, v187
	s_waitcnt vmcnt(0)
	v_mul_f32_e32 v66, v66, v172
	v_mul_f32_e32 v67, v67, v173
	v_mul_f32_e32 v68, v68, v174
	v_mul_f32_e32 v69, v69, v175
	v_mul_f32_e32 v70, v70, v172
	v_mul_f32_e32 v71, v71, v173
	v_mul_f32_e32 v72, v72, v174
	v_mul_f32_e32 v73, v73, v175
	v_mul_f32_e32 v74, v74, v172
	v_mul_f32_e32 v75, v75, v173
	v_mul_f32_e32 v76, v76, v174
	v_mul_f32_e32 v77, v77, v175
	v_mul_f32_e32 v78, v78, v172
	v_mul_f32_e32 v79, v79, v173
	v_mul_f32_e32 v80, v80, v174
	v_mul_f32_e32 v81, v81, v175
	v_mul_f32_e32 v82, v82, v176
	v_mul_f32_e32 v83, v83, v177
	v_mul_f32_e32 v84, v84, v178
	v_mul_f32_e32 v85, v85, v179
	v_mul_f32_e32 v86, v86, v176
	v_mul_f32_e32 v87, v87, v177
	v_mul_f32_e32 v88, v88, v178
	v_mul_f32_e32 v89, v89, v179
	v_mul_f32_e32 v90, v90, v176
	v_mul_f32_e32 v91, v91, v177
	v_mul_f32_e32 v92, v92, v178
	v_mul_f32_e32 v93, v93, v179
	v_mul_f32_e32 v94, v94, v176
	v_mul_f32_e32 v95, v95, v177
	v_mul_f32_e32 v96, v96, v178
	v_mul_f32_e32 v97, v97, v179
	v_mul_f32_e32 v98, v98, v180
	v_mul_f32_e32 v99, v99, v181
	v_mul_f32_e32 v100, v100, v182
	v_mul_f32_e32 v101, v101, v183
	v_mul_f32_e32 v102, v102, v180
	v_mul_f32_e32 v103, v103, v181
	v_mul_f32_e32 v104, v104, v182
	v_mul_f32_e32 v105, v105, v183
	v_mul_f32_e32 v106, v106, v180
	v_mul_f32_e32 v107, v107, v181
	v_mul_f32_e32 v108, v108, v182
	v_mul_f32_e32 v109, v109, v183
	v_mul_f32_e32 v110, v110, v180
	v_mul_f32_e32 v111, v111, v181
	v_mul_f32_e32 v112, v112, v182
	v_mul_f32_e32 v113, v113, v183
	v_mul_f32_e32 v114, v114, v184
	v_mul_f32_e32 v115, v115, v185
	v_mul_f32_e32 v116, v116, v186
	v_mul_f32_e32 v117, v117, v187
	v_mul_f32_e32 v118, v118, v184
	v_mul_f32_e32 v119, v119, v185
	v_mul_f32_e32 v120, v120, v186
	v_mul_f32_e32 v121, v121, v187
	v_mul_f32_e32 v122, v122, v184
	v_mul_f32_e32 v123, v123, v185
	v_mul_f32_e32 v124, v124, v186
	v_mul_f32_e32 v125, v125, v187
	v_mul_f32_e32 v126, v126, v184
	v_mul_f32_e32 v127, v127, v185
	v_mul_f32_e32 v128, v128, v186
	v_mul_f32_e32 v129, v129, v187
	v_mul_f32_e32 v66, v66, v136
	v_mul_f32_e32 v67, v67, v136
	v_mul_f32_e32 v68, v68, v136
	v_mul_f32_e32 v69, v69, v136
	v_mul_f32_e32 v70, v70, v137
	v_mul_f32_e32 v71, v71, v137
	v_mul_f32_e32 v72, v72, v137
	v_mul_f32_e32 v73, v73, v137
	v_mul_f32_e32 v74, v74, v138
	v_mul_f32_e32 v75, v75, v138
	v_mul_f32_e32 v76, v76, v138
	v_mul_f32_e32 v77, v77, v138
	v_mul_f32_e32 v78, v78, v139
	v_mul_f32_e32 v79, v79, v139
	v_mul_f32_e32 v80, v80, v139
	v_mul_f32_e32 v81, v81, v139
	v_mul_f32_e32 v82, v82, v136
	v_mul_f32_e32 v83, v83, v136
	v_mul_f32_e32 v84, v84, v136
	v_mul_f32_e32 v85, v85, v136
	v_mul_f32_e32 v86, v86, v137
	v_mul_f32_e32 v87, v87, v137
	v_mul_f32_e32 v88, v88, v137
	v_mul_f32_e32 v89, v89, v137
	v_mul_f32_e32 v90, v90, v138
	v_mul_f32_e32 v91, v91, v138
	v_mul_f32_e32 v92, v92, v138
	v_mul_f32_e32 v93, v93, v138
	v_mul_f32_e32 v94, v94, v139
	v_mul_f32_e32 v95, v95, v139
	v_mul_f32_e32 v96, v96, v139
	v_mul_f32_e32 v97, v97, v139
	v_mul_f32_e32 v98, v98, v136
	v_mul_f32_e32 v99, v99, v136
	v_mul_f32_e32 v100, v100, v136
	v_mul_f32_e32 v101, v101, v136
	v_mul_f32_e32 v102, v102, v137
	v_mul_f32_e32 v103, v103, v137
	v_mul_f32_e32 v104, v104, v137
	v_mul_f32_e32 v105, v105, v137
	v_mul_f32_e32 v106, v106, v138
	v_mul_f32_e32 v107, v107, v138
	v_mul_f32_e32 v108, v108, v138
	v_mul_f32_e32 v109, v109, v138
	v_mul_f32_e32 v110, v110, v139
	v_mul_f32_e32 v111, v111, v139
	v_mul_f32_e32 v112, v112, v139
	v_mul_f32_e32 v113, v113, v139
	v_mul_f32_e32 v114, v114, v136
	v_mul_f32_e32 v115, v115, v136
	v_mul_f32_e32 v116, v116, v136
	v_mul_f32_e32 v117, v117, v136
	v_mul_f32_e32 v118, v118, v137
	v_mul_f32_e32 v119, v119, v137
	v_mul_f32_e32 v120, v120, v137
	v_mul_f32_e32 v121, v121, v137
	v_mul_f32_e32 v122, v122, v138
	v_mul_f32_e32 v123, v123, v138
	v_mul_f32_e32 v124, v124, v138
	v_mul_f32_e32 v125, v125, v138
	v_mul_f32_e32 v126, v126, v139
	v_mul_f32_e32 v127, v127, v139
	v_mul_f32_e32 v128, v128, v139
	v_mul_f32_e32 v129, v129, v139
	s_movk_i32 s56, 0x170
	s_load_dwordx2 s[40:41], s[12:13], s56
.Lin2_t2_nonorm:
	s_cmp_eq_u32 s57, 2
	s_cbranch_scc1 .Lin2_t2_trans
	v_cvt_pk_bf16_f32 v66, v66, v70
	ds_write_b16 v229, v66
	ds_write_b16_d16_hi v229, v66 offset:32
	v_cvt_pk_bf16_f32 v74, v74, v78
	ds_write_b16 v229, v74 offset:64
	ds_write_b16_d16_hi v229, v74 offset:96
	v_cvt_pk_bf16_f32 v67, v67, v71
	ds_write_b16 v229, v67 offset:272
	ds_write_b16_d16_hi v229, v67 offset:304
	v_cvt_pk_bf16_f32 v75, v75, v79
	ds_write_b16 v229, v75 offset:336
	ds_write_b16_d16_hi v229, v75 offset:368
	v_cvt_pk_bf16_f32 v68, v68, v72
	ds_write_b16 v229, v68 offset:544
	ds_write_b16_d16_hi v229, v68 offset:576
	v_cvt_pk_bf16_f32 v76, v76, v80
	ds_write_b16 v229, v76 offset:608
	ds_write_b16_d16_hi v229, v76 offset:640
	v_cvt_pk_bf16_f32 v69, v69, v73
	ds_write_b16 v229, v69 offset:816
	ds_write_b16_d16_hi v229, v69 offset:848
	v_cvt_pk_bf16_f32 v77, v77, v81
	ds_write_b16 v229, v77 offset:880
	ds_write_b16_d16_hi v229, v77 offset:912
	v_cvt_pk_bf16_f32 v82, v82, v86
	ds_write_b16 v229, v82 offset:4352
	ds_write_b16_d16_hi v229, v82 offset:4384
	v_cvt_pk_bf16_f32 v90, v90, v94
	ds_write_b16 v229, v90 offset:4416
	ds_write_b16_d16_hi v229, v90 offset:4448
	v_cvt_pk_bf16_f32 v83, v83, v87
	ds_write_b16 v229, v83 offset:4624
	ds_write_b16_d16_hi v229, v83 offset:4656
	v_cvt_pk_bf16_f32 v91, v91, v95
	ds_write_b16 v229, v91 offset:4688
	ds_write_b16_d16_hi v229, v91 offset:4720
	v_cvt_pk_bf16_f32 v84, v84, v88
	ds_write_b16 v229, v84 offset:4896
	ds_write_b16_d16_hi v229, v84 offset:4928
	v_cvt_pk_bf16_f32 v92, v92, v96
	ds_write_b16 v229, v92 offset:4960
	ds_write_b16_d16_hi v229, v92 offset:4992
	v_cvt_pk_bf16_f32 v85, v85, v89
	ds_write_b16 v229, v85 offset:5168
	ds_write_b16_d16_hi v229, v85 offset:5200
	v_cvt_pk_bf16_f32 v93, v93, v97
	ds_write_b16 v229, v93 offset:5232
	ds_write_b16_d16_hi v229, v93 offset:5264
	v_cvt_pk_bf16_f32 v98, v98, v102
	ds_write_b16 v229, v98 offset:8704
	ds_write_b16_d16_hi v229, v98 offset:8736
	v_cvt_pk_bf16_f32 v106, v106, v110
	ds_write_b16 v229, v106 offset:8768
	ds_write_b16_d16_hi v229, v106 offset:8800
	v_cvt_pk_bf16_f32 v99, v99, v103
	ds_write_b16 v229, v99 offset:8976
	ds_write_b16_d16_hi v229, v99 offset:9008
	v_cvt_pk_bf16_f32 v107, v107, v111
	ds_write_b16 v229, v107 offset:9040
	ds_write_b16_d16_hi v229, v107 offset:9072
	v_cvt_pk_bf16_f32 v100, v100, v104
	ds_write_b16 v229, v100 offset:9248
	ds_write_b16_d16_hi v229, v100 offset:9280
	v_cvt_pk_bf16_f32 v108, v108, v112
	ds_write_b16 v229, v108 offset:9312
	ds_write_b16_d16_hi v229, v108 offset:9344
	v_cvt_pk_bf16_f32 v101, v101, v105
	ds_write_b16 v229, v101 offset:9520
	ds_write_b16_d16_hi v229, v101 offset:9552
	v_cvt_pk_bf16_f32 v109, v109, v113
	ds_write_b16 v229, v109 offset:9584
	ds_write_b16_d16_hi v229, v109 offset:9616
	v_cvt_pk_bf16_f32 v114, v114, v118
	ds_write_b16 v229, v114 offset:13056
	ds_write_b16_d16_hi v229, v114 offset:13088
	v_cvt_pk_bf16_f32 v122, v122, v126
	ds_write_b16 v229, v122 offset:13120
	ds_write_b16_d16_hi v229, v122 offset:13152
	v_cvt_pk_bf16_f32 v115, v115, v119
	ds_write_b16 v229, v115 offset:13328
	ds_write_b16_d16_hi v229, v115 offset:13360
	v_cvt_pk_bf16_f32 v123, v123, v127
	ds_write_b16 v229, v123 offset:13392
	ds_write_b16_d16_hi v229, v123 offset:13424
	v_cvt_pk_bf16_f32 v116, v116, v120
	ds_write_b16 v229, v116 offset:13600
	ds_write_b16_d16_hi v229, v116 offset:13632
	v_cvt_pk_bf16_f32 v124, v124, v128
	ds_write_b16 v229, v124 offset:13664
	ds_write_b16_d16_hi v229, v124 offset:13696
	v_cvt_pk_bf16_f32 v117, v117, v121
	ds_write_b16 v229, v117 offset:13872
	ds_write_b16_d16_hi v229, v117 offset:13904
	v_cvt_pk_bf16_f32 v125, v125, v129
	ds_write_b16 v229, v125 offset:13936
	ds_write_b16_d16_hi v229, v125 offset:13968
	s_mul_i32 s0, s53, 0x2500
	s_lshl_b32 s56, s52, 8
	s_add_i32 s0, s0, s56
	s_waitcnt lgkmcnt(0)
	s_add_u32 s58, s40, s0
	s_addc_u32 s59, s41, 0
	s_mov_b32 s56, 0x25000
	v_mov_b32_e32 v241, v232
	s_branch .Lin2_t2_store
.Lin2_t2_trans:
	v_cvt_pk_bf16_f32 v66, v66, v67
	v_cvt_pk_bf16_f32 v67, v68, v69
	ds_write_b64 v230, v[66:67]
	v_cvt_pk_bf16_f32 v70, v70, v71
	v_cvt_pk_bf16_f32 v71, v72, v73
	ds_write_b64 v230, v[70:71] offset:4352
	v_cvt_pk_bf16_f32 v74, v74, v75
	v_cvt_pk_bf16_f32 v75, v76, v77
	ds_write_b64 v230, v[74:75] offset:8704
	v_cvt_pk_bf16_f32 v78, v78, v79
	v_cvt_pk_bf16_f32 v79, v80, v81
	ds_write_b64 v230, v[78:79] offset:13056
	v_cvt_pk_bf16_f32 v82, v82, v83
	v_cvt_pk_bf16_f32 v83, v84, v85
	ds_write_b64 v230, v[82:83] offset:32
	v_cvt_pk_bf16_f32 v86, v86, v87
	v_cvt_pk_bf16_f32 v87, v88, v89
	ds_write_b64 v230, v[86:87] offset:4384
	v_cvt_pk_bf16_f32 v90, v90, v91
	v_cvt_pk_bf16_f32 v91, v92, v93
	ds_write_b64 v230, v[90:91] offset:8736
	v_cvt_pk_bf16_f32 v94, v94, v95
	v_cvt_pk_bf16_f32 v95, v96, v97
	ds_write_b64 v230, v[94:95] offset:13088
	v_cvt_pk_bf16_f32 v98, v98, v99
	v_cvt_pk_bf16_f32 v99, v100, v101
	ds_write_b64 v230, v[98:99] offset:64
	v_cvt_pk_bf16_f32 v102, v102, v103
	v_cvt_pk_bf16_f32 v103, v104, v105
	ds_write_b64 v230, v[102:103] offset:4416
	v_cvt_pk_bf16_f32 v106, v106, v107
	v_cvt_pk_bf16_f32 v107, v108, v109
	ds_write_b64 v230, v[106:107] offset:8768
	v_cvt_pk_bf16_f32 v110, v110, v111
	v_cvt_pk_bf16_f32 v111, v112, v113
	ds_write_b64 v230, v[110:111] offset:13120
	v_cvt_pk_bf16_f32 v114, v114, v115
	v_cvt_pk_bf16_f32 v115, v116, v117
	ds_write_b64 v230, v[114:115] offset:96
	v_cvt_pk_bf16_f32 v118, v118, v119
	v_cvt_pk_bf16_f32 v119, v120, v121
	ds_write_b64 v230, v[118:119] offset:4448
	v_cvt_pk_bf16_f32 v122, v122, v123
	v_cvt_pk_bf16_f32 v123, v124, v125
	ds_write_b64 v230, v[122:123] offset:8800
	v_cvt_pk_bf16_f32 v126, v126, v127
	v_cvt_pk_bf16_f32 v127, v128, v129
	ds_write_b64 v230, v[126:127] offset:13152
	s_lshr_b32 s0, s53, 11
	s_lshl_b32 s0, s0, 1
	s_and_b32 s56, s52, 1
	s_add_i32 s0, s0, s56
	s_lshl_b32 s0, s0, 19
	s_lshr_b32 s56, s53, 7
	s_and_b32 s56, s56, 15
	s_lshl_b32 s56, s56, 8
	s_add_i32 s0, s0, s56
	s_waitcnt lgkmcnt(0)
	s_add_u32 s58, s40, s0
	s_addc_u32 s59, s41, 0
	s_mov_b32 s56, 0x10000
	v_mov_b32_e32 v241, v233
.Lin2_t2_store:
	s_waitcnt lgkmcnt(0)
	s_barrier
	ds_read_b128 v[172:175], v231
	ds_read_b128 v[176:179], v231 offset:4352
	ds_read_b128 v[180:183], v231 offset:8704
	ds_read_b128 v[184:187], v231 offset:13056
	ds_read_b128 v[196:199], v231 offset:17408
	ds_read_b128 v[200:203], v231 offset:21760
	ds_read_b128 v[204:207], v231 offset:26112
	ds_read_b128 v[212:215], v231 offset:30464
	s_waitcnt lgkmcnt(7)
	global_store_dwordx4 v241, v[172:175], s[58:59]
	s_add_u32 s58, s58, s56
	s_addc_u32 s59, s59, 0
	s_waitcnt lgkmcnt(6)
	global_store_dwordx4 v241, v[176:179], s[58:59]
	s_add_u32 s58, s58, s56
	s_addc_u32 s59, s59, 0
	s_waitcnt lgkmcnt(5)
	global_store_dwordx4 v241, v[180:183], s[58:59]
	s_add_u32 s58, s58, s56
	s_addc_u32 s59, s59, 0
	s_waitcnt lgkmcnt(4)
	global_store_dwordx4 v241, v[184:187], s[58:59]
	s_add_u32 s58, s58, s56
	s_addc_u32 s59, s59, 0
	s_waitcnt lgkmcnt(3)
	global_store_dwordx4 v241, v[196:199], s[58:59]
	s_add_u32 s58, s58, s56
	s_addc_u32 s59, s59, 0
	s_waitcnt lgkmcnt(2)
	global_store_dwordx4 v241, v[200:203], s[58:59]
	s_add_u32 s58, s58, s56
	s_addc_u32 s59, s59, 0
	s_waitcnt lgkmcnt(1)
	global_store_dwordx4 v241, v[204:207], s[58:59]
	s_add_u32 s58, s58, s56
	s_addc_u32 s59, s59, 0
	s_waitcnt lgkmcnt(0)
	global_store_dwordx4 v241, v[212:215], s[58:59]
	s_barrier
	s_add_i32 s55, s55, 1
	s_cmp_lt_u32 s55, 2
	s_cbranch_scc1 .Lin2_tile
	s_add_i32 s21, s21, s72
	s_cmpk_lt_i32 s21, 0x200
	s_cbranch_scc1 .Lin2_vloop
.Lin2_done:
	s_add_i32 s21, s60, 0x800
	s_mov_b32 s20, s21
	v_readlane_b32 s8, v209, 21
	s_addk_i32 s8, 0x800
	s_cmpk_gt_i32 s21, 0x9bf
	s_cbranch_scc1 .LBB0_361
	s_branch .LBB0_367

.LBB0_597:
	s_andn2_b64 vcc, exec, s[40:41]
	s_cbranch_vccnz .LBB0_488
	s_ashr_i32 s22, s8, 31
	s_lshr_b32 s22, s22, 30
	s_load_dwordx2 s[20:21], s[12:13], 0x18
	s_add_i32 s22, s8, s22
	s_waitcnt lgkmcnt(0)
	v_mov_b32_e32 v4, v131
	s_and_b32 s23, s22, 0x7ffffc
	s_lshl_b32 s22, s22, 4
	s_and_b32 s40, s22, 0xffffffc0
	v_and_b32_e32 v9, 15, v4
	s_sub_i32 s23, s8, s23
	v_lshl_or_b32 v0, v9, 2, s40
	s_movk_i32 s22, 0x1218
	s_ashr_i32 s41, s40, 31
	s_lshl_b32 s42, s23, 9
	v_cmp_gt_i32_e32 vcc, s22, v0
	s_lshl_b64 s[22:23], s[40:41], 2
	v_ashrrev_i32_e32 v0, 2, v4
	s_add_u32 s20, s20, s22
	v_and_b32_e32 v11, -4, v0
	s_addc_u32 s21, s21, s23
	v_lshlrev_b32_e32 v0, 4, v9
	v_add_u32_e32 v12, s42, v11
	v_lshl_add_u64 v[2:3], s[20:21], 0, v[0:1]
	v_mov_b32_e32 v6, 0
	v_mov_b32_e32 v5, 0
	v_mov_b32_e32 v7, 0
	v_mov_b32_e32 v8, 0
	v_mov_b32_e32 v10, 0
	v_mov_b32_e32 v13, 0
	v_mov_b32_e32 v14, 0
	v_mov_b32_e32 v15, 0
	v_mov_b32_e32 v16, 0
	v_mov_b32_e32 v17, 0
	v_mov_b32_e32 v18, 0
	v_mov_b32_e32 v19, 0
	v_mov_b32_e32 v20, 0
	v_mov_b32_e32 v24, 0
	v_mov_b32_e32 v27, 0
	v_mov_b32_e32 v28, 0
	v_mov_b32_e32 v21, 0
	v_mov_b32_e32 v22, 0
	v_mov_b32_e32 v23, 0
	v_mov_b32_e32 v25, 0
	v_mov_b32_e32 v26, 0
	v_mov_b32_e32 v29, 0
	v_mov_b32_e32 v30, 0
	v_mov_b32_e32 v31, 0
	v_mov_b32_e32 v32, 0
	v_mov_b32_e32 v33, 0
	v_mov_b32_e32 v34, 0
	v_mov_b32_e32 v35, 0
	v_mov_b32_e32 v36, 0
	v_mov_b32_e32 v40, 0
	v_mov_b32_e32 v42, 0
	v_mov_b32_e32 v44, 0
	v_mov_b32_e32 v37, 0
	v_mov_b32_e32 v38, 0
	v_mov_b32_e32 v39, 0
	v_mov_b32_e32 v41, 0
	v_mov_b32_e32 v43, 0
	v_mov_b32_e32 v45, 0
	v_mov_b32_e32 v46, 0
	v_mov_b32_e32 v47, 0
	v_mov_b32_e32 v48, 0
	v_mov_b32_e32 v49, 0
	v_mov_b32_e32 v50, 0
	v_mov_b32_e32 v51, 0
	v_mov_b32_e32 v52, 0
	v_mov_b32_e32 v56, 0
	v_mov_b32_e32 v58, 0
	v_mov_b32_e32 v60, 0
	v_mov_b32_e32 v53, 0
	v_mov_b32_e32 v54, 0
	v_mov_b32_e32 v55, 0
	v_mov_b32_e32 v57, 0
	v_mov_b32_e32 v59, 0
	v_mov_b32_e32 v61, 0
	v_mov_b32_e32 v62, 0
	v_mov_b32_e32 v63, 0
	v_mov_b32_e32 v64, 0
	v_mov_b32_e32 v65, 0
	v_mov_b32_e32 v66, 0
	v_mov_b32_e32 v67, 0
	v_mov_b32_e32 v68, 0
	v_mov_b32_e32 v72, 0
	v_mov_b32_e32 v74, 0
	v_mov_b32_e32 v76, 0
	v_mov_b32_e32 v69, 0
	v_mov_b32_e32 v70, 0
	v_mov_b32_e32 v71, 0
	v_mov_b32_e32 v73, 0
	v_mov_b32_e32 v75, 0
	v_mov_b32_e32 v77, 0
	v_mov_b32_e32 v78, 0
	v_mov_b32_e32 v79, 0
	v_mov_b32_e32 v80, 0
	v_mov_b32_e32 v81, 0
	v_mov_b32_e32 v82, 0
	v_mov_b32_e32 v83, 0
	v_mov_b32_e32 v84, 0
	v_mov_b32_e32 v88, 0
	v_mov_b32_e32 v90, 0
	v_mov_b32_e32 v92, 0
	v_mov_b32_e32 v85, 0
	v_mov_b32_e32 v86, 0
	v_mov_b32_e32 v87, 0
	v_mov_b32_e32 v89, 0
	v_mov_b32_e32 v91, 0
	v_mov_b32_e32 v93, 0
	v_mov_b32_e32 v94, 0
	v_mov_b32_e32 v95, 0
	v_mov_b32_e32 v96, 0
	v_mov_b32_e32 v97, 0
	v_mov_b32_e32 v98, 0
	v_mov_b32_e32 v99, 0
	v_mov_b32_e32 v100, 0
	v_mov_b32_e32 v104, 0
	v_mov_b32_e32 v106, 0
	v_mov_b32_e32 v108, 0
	v_mov_b32_e32 v101, 0
	v_mov_b32_e32 v102, 0
	v_mov_b32_e32 v103, 0
	v_mov_b32_e32 v105, 0
	v_mov_b32_e32 v107, 0
	v_mov_b32_e32 v109, 0
	v_mov_b32_e32 v110, 0
	v_mov_b32_e32 v111, 0
	v_mov_b32_e32 v112, 0
	v_mov_b32_e32 v113, 0
	v_mov_b32_e32 v114, 0
	v_mov_b32_e32 v115, 0
	v_mov_b32_e32 v116, 0
	v_mov_b32_e32 v120, 0
	v_mov_b32_e32 v122, 0
	v_mov_b32_e32 v124, 0
	v_mov_b32_e32 v117, 0
	v_mov_b32_e32 v118, 0
	v_mov_b32_e32 v119, 0
	v_mov_b32_e32 v121, 0
	v_mov_b32_e32 v123, 0
	v_mov_b32_e32 v125, 0
	v_mov_b32_e32 v126, 0
	v_mov_b32_e32 v127, 0
	v_mov_b32_e32 v128, 0
	v_mov_b32_e32 v129, 0
	v_mov_b32_e32 v133, 0
	v_mov_b32_e32 v135, 0
	v_mov_b32_e32 v136, 0
	v_mov_b32_e32 v137, 0
	v_mov_b32_e32 v138, 0
	v_mov_b32_e32 v139, 0
	s_load_dwordx2 s[44:45], s[12:13], 0x108
	s_movk_i32 s0, 0x4860
	s_and_saveexec_b64 s[48:49], vcc
	s_cbranch_execz .Lp0win_skip
	v_mad_i64_i32 v[196:197], s[20:21], v12, s0, v[2:3]
	global_load_dwordx4 v[212:215], v[196:197], off
	v_or_b32_e32 v249, 1, v12
	v_mad_i64_i32 v[198:199], s[20:21], v249, s0, v[2:3]
	global_load_dwordx4 v[216:219], v[198:199], off
	v_or_b32_e32 v250, 2, v12
	v_mad_i64_i32 v[200:201], s[20:21], v250, s0, v[2:3]
	global_load_dwordx4 v[220:223], v[200:201], off
	v_or_b32_e32 v251, 3, v12
	v_mad_i64_i32 v[202:203], s[20:21], v251, s0, v[2:3]
	global_load_dwordx4 v[224:227], v[202:203], off
	v_add_u32_e32 v252, 64, v12
	v_mad_i64_i32 v[204:205], s[20:21], v252, s0, v[2:3]
	global_load_dwordx4 v[228:231], v[204:205], off
	v_add_u32_e32 v253, 0x41, v12
	v_mad_i64_i32 v[206:207], s[20:21], v253, s0, v[2:3]
	global_load_dwordx4 v[232:235], v[206:207], off
	v_add_u32_e32 v254, 0x42, v12
	v_mad_i64_i32 v[244:245], s[20:21], v254, s0, v[2:3]
	global_load_dwordx4 v[236:239], v[244:245], off
	v_add_u32_e32 v255, 0x43, v12
	v_mad_i64_i32 v[246:247], s[20:21], v255, s0, v[2:3]
	global_load_dwordx4 v[240:243], v[246:247], off
	s_waitcnt vmcnt(7)
	v_cvt_pk_bf16_f32 v10, v212, s0
	v_cvt_pk_bf16_f32 v8, v213, s0
	v_cvt_pk_bf16_f32 v7, v214, s0
	v_cvt_pk_bf16_f32 v5, v215, s0
	s_waitcnt vmcnt(6)
	v_cvt_pk_bf16_f32 v15, v216, s0
	v_cvt_pk_bf16_f32 v14, v217, s0
	v_cvt_pk_bf16_f32 v13, v218, s0
	v_cvt_pk_bf16_f32 v6, v219, s0
	s_waitcnt vmcnt(5)
	v_cvt_pk_bf16_f32 v20, v220, s0
	v_cvt_pk_bf16_f32 v19, v221, s0
	v_cvt_pk_bf16_f32 v18, v222, s0
	v_cvt_pk_bf16_f32 v17, v223, s0
	s_waitcnt vmcnt(4)
	v_cvt_pk_bf16_f32 v28, v224, s0
	v_cvt_pk_bf16_f32 v27, v225, s0
	v_cvt_pk_bf16_f32 v24, v226, s0
	v_cvt_pk_bf16_f32 v16, v227, s0
	s_waitcnt vmcnt(3)
	v_cvt_pk_bf16_f32 v26, v228, s0
	v_cvt_pk_bf16_f32 v25, v229, s0
	v_cvt_pk_bf16_f32 v23, v230, s0
	v_cvt_pk_bf16_f32 v22, v231, s0
	s_waitcnt vmcnt(2)
	v_cvt_pk_bf16_f32 v31, v232, s0
	v_cvt_pk_bf16_f32 v30, v233, s0
	v_cvt_pk_bf16_f32 v29, v234, s0
	v_cvt_pk_bf16_f32 v21, v235, s0
	s_waitcnt vmcnt(1)
	v_cvt_pk_bf16_f32 v36, v236, s0
	v_cvt_pk_bf16_f32 v35, v237, s0
	v_cvt_pk_bf16_f32 v34, v238, s0
	v_cvt_pk_bf16_f32 v33, v239, s0
	s_waitcnt vmcnt(0)
	v_cvt_pk_bf16_f32 v44, v240, s0
	v_cvt_pk_bf16_f32 v42, v241, s0
	v_cvt_pk_bf16_f32 v40, v242, s0
	v_cvt_pk_bf16_f32 v32, v243, s0
	v_add_u32_e32 v248, 0x80, v12
	v_mad_i64_i32 v[196:197], s[20:21], v248, s0, v[2:3]
	global_load_dwordx4 v[212:215], v[196:197], off
	v_add_u32_e32 v249, 0x81, v12
	v_mad_i64_i32 v[198:199], s[20:21], v249, s0, v[2:3]
	global_load_dwordx4 v[216:219], v[198:199], off
	v_add_u32_e32 v250, 0x82, v12
	v_mad_i64_i32 v[200:201], s[20:21], v250, s0, v[2:3]
	global_load_dwordx4 v[220:223], v[200:201], off
	v_add_u32_e32 v251, 0x83, v12
	v_mad_i64_i32 v[202:203], s[20:21], v251, s0, v[2:3]
	global_load_dwordx4 v[224:227], v[202:203], off
	v_add_u32_e32 v252, 0xc0, v12
	v_mad_i64_i32 v[204:205], s[20:21], v252, s0, v[2:3]
	global_load_dwordx4 v[228:231], v[204:205], off
	v_add_u32_e32 v253, 0xc1, v12
	v_mad_i64_i32 v[206:207], s[20:21], v253, s0, v[2:3]
	global_load_dwordx4 v[232:235], v[206:207], off
	v_add_u32_e32 v254, 0xc2, v12
	v_mad_i64_i32 v[244:245], s[20:21], v254, s0, v[2:3]
	global_load_dwordx4 v[236:239], v[244:245], off
	v_add_u32_e32 v255, 0xc3, v12
	v_mad_i64_i32 v[246:247], s[20:21], v255, s0, v[2:3]
	global_load_dwordx4 v[240:243], v[246:247], off
	s_waitcnt vmcnt(7)
	v_cvt_pk_bf16_f32 v43, v212, s0
	v_cvt_pk_bf16_f32 v41, v213, s0
	v_cvt_pk_bf16_f32 v39, v214, s0
	v_cvt_pk_bf16_f32 v38, v215, s0
	s_waitcnt vmcnt(6)
	v_cvt_pk_bf16_f32 v47, v216, s0
	v_cvt_pk_bf16_f32 v46, v217, s0
	v_cvt_pk_bf16_f32 v45, v218, s0
	v_cvt_pk_bf16_f32 v37, v219, s0
	s_waitcnt vmcnt(5)
	v_cvt_pk_bf16_f32 v52, v220, s0
	v_cvt_pk_bf16_f32 v51, v221, s0
	v_cvt_pk_bf16_f32 v50, v222, s0
	v_cvt_pk_bf16_f32 v49, v223, s0
	s_waitcnt vmcnt(4)
	v_cvt_pk_bf16_f32 v60, v224, s0
	v_cvt_pk_bf16_f32 v58, v225, s0
	v_cvt_pk_bf16_f32 v56, v226, s0
	v_cvt_pk_bf16_f32 v48, v227, s0
	s_waitcnt vmcnt(3)
	v_cvt_pk_bf16_f32 v59, v228, s0
	v_cvt_pk_bf16_f32 v57, v229, s0
	v_cvt_pk_bf16_f32 v55, v230, s0
	v_cvt_pk_bf16_f32 v54, v231, s0
	s_waitcnt vmcnt(2)
	v_cvt_pk_bf16_f32 v63, v232, s0
	v_cvt_pk_bf16_f32 v62, v233, s0
	v_cvt_pk_bf16_f32 v61, v234, s0
	v_cvt_pk_bf16_f32 v53, v235, s0
	s_waitcnt vmcnt(1)
	v_cvt_pk_bf16_f32 v68, v236, s0
	v_cvt_pk_bf16_f32 v67, v237, s0
	v_cvt_pk_bf16_f32 v66, v238, s0
	v_cvt_pk_bf16_f32 v65, v239, s0
	s_waitcnt vmcnt(0)
	v_cvt_pk_bf16_f32 v76, v240, s0
	v_cvt_pk_bf16_f32 v74, v241, s0
	v_cvt_pk_bf16_f32 v72, v242, s0
	v_cvt_pk_bf16_f32 v64, v243, s0
	v_add_u32_e32 v248, 0x100, v12
	v_mad_i64_i32 v[196:197], s[20:21], v248, s0, v[2:3]
	global_load_dwordx4 v[212:215], v[196:197], off
	v_add_u32_e32 v249, 0x101, v12
	v_mad_i64_i32 v[198:199], s[20:21], v249, s0, v[2:3]
	global_load_dwordx4 v[216:219], v[198:199], off
	v_add_u32_e32 v250, 0x102, v12
	v_mad_i64_i32 v[200:201], s[20:21], v250, s0, v[2:3]
	global_load_dwordx4 v[220:223], v[200:201], off
	v_add_u32_e32 v251, 0x103, v12
	v_mad_i64_i32 v[202:203], s[20:21], v251, s0, v[2:3]
	global_load_dwordx4 v[224:227], v[202:203], off
	v_add_u32_e32 v252, 0x140, v12
	v_mad_i64_i32 v[204:205], s[20:21], v252, s0, v[2:3]
	global_load_dwordx4 v[228:231], v[204:205], off
	v_add_u32_e32 v253, 0x141, v12
	v_mad_i64_i32 v[206:207], s[20:21], v253, s0, v[2:3]
	global_load_dwordx4 v[232:235], v[206:207], off
	v_add_u32_e32 v254, 0x142, v12
	v_mad_i64_i32 v[244:245], s[20:21], v254, s0, v[2:3]
	global_load_dwordx4 v[236:239], v[244:245], off
	v_add_u32_e32 v255, 0x143, v12
	v_mad_i64_i32 v[246:247], s[20:21], v255, s0, v[2:3]
	global_load_dwordx4 v[240:243], v[246:247], off
	s_waitcnt vmcnt(7)
	v_cvt_pk_bf16_f32 v75, v212, s0
	v_cvt_pk_bf16_f32 v73, v213, s0
	v_cvt_pk_bf16_f32 v71, v214, s0
	v_cvt_pk_bf16_f32 v70, v215, s0
	s_waitcnt vmcnt(6)
	v_cvt_pk_bf16_f32 v79, v216, s0
	v_cvt_pk_bf16_f32 v78, v217, s0
	v_cvt_pk_bf16_f32 v77, v218, s0
	v_cvt_pk_bf16_f32 v69, v219, s0
	s_waitcnt vmcnt(5)
	v_cvt_pk_bf16_f32 v84, v220, s0
	v_cvt_pk_bf16_f32 v83, v221, s0
	v_cvt_pk_bf16_f32 v82, v222, s0
	v_cvt_pk_bf16_f32 v81, v223, s0
	s_waitcnt vmcnt(4)
	v_cvt_pk_bf16_f32 v92, v224, s0
	v_cvt_pk_bf16_f32 v90, v225, s0
	v_cvt_pk_bf16_f32 v88, v226, s0
	v_cvt_pk_bf16_f32 v80, v227, s0
	s_waitcnt vmcnt(3)
	v_cvt_pk_bf16_f32 v91, v228, s0
	v_cvt_pk_bf16_f32 v89, v229, s0
	v_cvt_pk_bf16_f32 v87, v230, s0
	v_cvt_pk_bf16_f32 v86, v231, s0
	s_waitcnt vmcnt(2)
	v_cvt_pk_bf16_f32 v95, v232, s0
	v_cvt_pk_bf16_f32 v94, v233, s0
	v_cvt_pk_bf16_f32 v93, v234, s0
	v_cvt_pk_bf16_f32 v85, v235, s0
	s_waitcnt vmcnt(1)
	v_cvt_pk_bf16_f32 v100, v236, s0
	v_cvt_pk_bf16_f32 v99, v237, s0
	v_cvt_pk_bf16_f32 v98, v238, s0
	v_cvt_pk_bf16_f32 v97, v239, s0
	s_waitcnt vmcnt(0)
	v_cvt_pk_bf16_f32 v108, v240, s0
	v_cvt_pk_bf16_f32 v106, v241, s0
	v_cvt_pk_bf16_f32 v104, v242, s0
	v_cvt_pk_bf16_f32 v96, v243, s0
	v_add_u32_e32 v248, 0x180, v12
	v_mad_i64_i32 v[196:197], s[20:21], v248, s0, v[2:3]
	global_load_dwordx4 v[212:215], v[196:197], off
	v_add_u32_e32 v249, 0x181, v12
	v_mad_i64_i32 v[198:199], s[20:21], v249, s0, v[2:3]
	global_load_dwordx4 v[216:219], v[198:199], off
	v_add_u32_e32 v250, 0x182, v12
	v_mad_i64_i32 v[200:201], s[20:21], v250, s0, v[2:3]
	global_load_dwordx4 v[220:223], v[200:201], off
	v_add_u32_e32 v251, 0x183, v12
	v_mad_i64_i32 v[202:203], s[20:21], v251, s0, v[2:3]
	global_load_dwordx4 v[224:227], v[202:203], off
	v_add_u32_e32 v252, 0x1c0, v12
	v_mad_i64_i32 v[204:205], s[20:21], v252, s0, v[2:3]
	global_load_dwordx4 v[228:231], v[204:205], off
	v_add_u32_e32 v253, 0x1c1, v12
	v_mad_i64_i32 v[206:207], s[20:21], v253, s0, v[2:3]
	global_load_dwordx4 v[232:235], v[206:207], off
	v_add_u32_e32 v254, 0x1c2, v12
	v_mad_i64_i32 v[244:245], s[20:21], v254, s0, v[2:3]
	global_load_dwordx4 v[236:239], v[244:245], off
	v_add_u32_e32 v255, 0x1c3, v12
	v_mad_i64_i32 v[246:247], s[20:21], v255, s0, v[2:3]
	global_load_dwordx4 v[240:243], v[246:247], off
	s_waitcnt vmcnt(7)
	v_cvt_pk_bf16_f32 v107, v212, s0
	v_cvt_pk_bf16_f32 v105, v213, s0
	v_cvt_pk_bf16_f32 v103, v214, s0
	v_cvt_pk_bf16_f32 v102, v215, s0
	s_waitcnt vmcnt(6)
	v_cvt_pk_bf16_f32 v111, v216, s0
	v_cvt_pk_bf16_f32 v110, v217, s0
	v_cvt_pk_bf16_f32 v109, v218, s0
	v_cvt_pk_bf16_f32 v101, v219, s0
	s_waitcnt vmcnt(5)
	v_cvt_pk_bf16_f32 v116, v220, s0
	v_cvt_pk_bf16_f32 v115, v221, s0
	v_cvt_pk_bf16_f32 v114, v222, s0
	v_cvt_pk_bf16_f32 v113, v223, s0
	s_waitcnt vmcnt(4)
	v_cvt_pk_bf16_f32 v124, v224, s0
	v_cvt_pk_bf16_f32 v122, v225, s0
	v_cvt_pk_bf16_f32 v120, v226, s0
	v_cvt_pk_bf16_f32 v112, v227, s0
	s_waitcnt vmcnt(3)
	v_cvt_pk_bf16_f32 v123, v228, s0
	v_cvt_pk_bf16_f32 v121, v229, s0
	v_cvt_pk_bf16_f32 v119, v230, s0
	v_cvt_pk_bf16_f32 v118, v231, s0
	s_waitcnt vmcnt(2)
	v_cvt_pk_bf16_f32 v127, v232, s0
	v_cvt_pk_bf16_f32 v126, v233, s0
	v_cvt_pk_bf16_f32 v125, v234, s0
	v_cvt_pk_bf16_f32 v117, v235, s0
	s_waitcnt vmcnt(1)
	v_cvt_pk_bf16_f32 v136, v236, s0
	v_cvt_pk_bf16_f32 v135, v237, s0
	v_cvt_pk_bf16_f32 v133, v238, s0
	v_cvt_pk_bf16_f32 v129, v239, s0
	s_waitcnt vmcnt(0)
	v_cvt_pk_bf16_f32 v139, v240, s0
	v_cvt_pk_bf16_f32 v138, v241, s0
	v_cvt_pk_bf16_f32 v137, v242, s0
	v_cvt_pk_bf16_f32 v128, v243, s0
.Lp0win_skip:
	s_or_b64 exec, exec, s[48:49]
	s_branch .LBB0_487
